# rwkv pass 2 (three levels) rewritten: each step's matrices loaded a whole step ahead into a second register set; lru3 carry fold batched; mode-1 sums vectorised; lora decay simplified
# speedup vs baseline: 1.0149x; 1.0149x over previous
; template <bool HAS_C, bool STORE_STEPS>
; __device__ __forceinline__ void chain16(f32x4 (&acc)[4], const float* Mb, size_t mstride, float* Cb, size_t cstride, int nsteps) {
;     f32x4 mc[16];
; #pragma unroll
;     for (int i = 0; i < 16; ++i) mc[i] = *(const f32x4*)(Mb + (size_t)i * 64);
;     f32x4 qn[4];
;     if (HAS_C) {
; #pragma unroll
;         for (int j = 0; j < 4; ++j) qn[j] = *(const f32x4*)(Cb + 4 * j);
;     }
;     for (int c = 0; c < nsteps; ++c) {
;         float* cp = Cb + (size_t)c * cstride;
;         f32x4 q[4];
;         if (HAS_C) {
; #pragma unroll
;             for (int j = 0; j < 4; ++j) q[j] = qn[j];
;             const float* cn = Cb + (size_t)(c + 1 < nsteps ? c + 1 : c) * cstride;
; #pragma unroll
;             for (int j = 0; j < 4; ++j) qn[j] = *(const f32x4*)(cn + 4 * j);
;         }
;         f32x4 mn[16];
;         const float* Mn = Mb + (size_t)(c + 1 < nsteps ? c + 1 : c) * mstride;
; #pragma unroll
;         for (int i = 0; i < 16; ++i) mn[i] = *(const f32x4*)(Mn + (size_t)i * 64);
;         if (STORE_STEPS) {
; #pragma unroll
;             for (int j = 0; j < 4; ++j) *(f32x4*)(cp + 4 * j) = (f32x4){acc[0][j], acc[1][j], acc[2][j], acc[3][j]};
; __device__ __forceinline__ void stage_rwkv_pass2(const Params& P, int level) {
;     ...
;         for (int it0 = spread ? (wave < 2 ? (int)blockIdx.x : P2_NG * 32) : gw; it0 < P2_NG * 8 * 4; it0 += spread ? P2_NG * 32 : ngw) {
;             int it = it0;
;             if (spread) { const int x = blockIdx.x & 7, j = blockIdx.x >> 3, idx = wave * 32 + j; it = ((idx >> 2) * 8 + x) * 4 + (idx & 3); }
;             const int g = it >> 5, h = (it >> 2) & 7, s = it & 3, v = 16 * s + rho;
;             const float* sg = CG + ((size_t)g * 8 + h) * 4096 + (size_t)v * 64 + 16 * g4;
;             f32x4 q[4];
; #pragma unroll
;             for (int j = 0; j < 4; ++j) q[j] = *(const f32x4*)(sg + 4 * j);
; #pragma unroll
;             for (int n = 0; n < 4; ++n) acc[n] = (f32x4){q[0][n], q[1][n], q[2][n], q[3][n]};
;             const float* Mb = MCM + ((size_t)(g * P2_GS) * 8 + h) * 4096 + (size_t)(16 * g4) * 64 + 4 * rho;
;             float* Cb = MCC + ((size_t)(g * P2_GS) * 8 + h) * 4096 + (size_t)v * 64 + 16 * g4;
;             chain16<true, true>(acc, Mb, 32768, Cb, 32768, P2_GS);
.LBB0_214:
	s_andn2_b64 vcc, exec, s[0:1]
	s_cbranch_vccnz .LBB0_220
	v_readfirstlane_b32 s0, v211
	s_lshr_b32 s11, s0, 6
	s_cmpk_eq_i32 s62, 0x100
	s_cselect_b32 s12, 1, 0
	s_cbranch_scc0 .Lp2l2_gen
	s_cmp_lt_u32 s11, 2
	s_cselect_b32 s8, s54, 0x200
	s_movk_i32 s16, 0x200
	s_branch .Lp2l2_go
.Lp2l2_gen:
	s_add_i32 s8, s55, s11
	s_mov_b32 s16, s58
.Lp2l2_go:
	s_cmpk_gt_i32 s8, 0x1ff
	s_cbranch_scc1 .Lp2l2_end
	v_and_b32_e32 v146, 63, v211
	v_and_b32_e32 v147, 15, v146
	v_lshrrev_b32_e32 v148, 4, v146
	v_lshlrev_b32_e32 v144, 12, v148
	v_lshl_add_u32 v144, v147, 4, v144
	v_lshlrev_b32_e32 v145, 6, v148
	v_lshl_add_u32 v145, v147, 8, v145
.Lp2l2_item:
	s_mov_b32 s13, s8
	s_cmp_eq_u32 s12, 0
	s_cbranch_scc1 .Lp2l2_map
	s_and_b32 s14, s54, 7
	s_lshr_b32 s15, s54, 3
	s_lshl_b32 s13, s11, 5
	s_add_i32 s15, s13, s15
	s_lshr_b32 s13, s15, 2
	s_lshl_b32 s13, s13, 3
	s_add_i32 s13, s13, s14
	s_lshl_b32 s13, s13, 2
	s_and_b32 s15, s15, 3
	s_add_i32 s13, s13, s15
.Lp2l2_map:
	s_lshr_b32 s14, s13, 5
	s_bfe_u32 s15, s13, 0x30002
	s_and_b32 s17, s13, 3
	s_lshl_b32 s19, s17, 12
	s_lshl_b32 s18, s14, 3
	s_add_i32 s18, s18, s15
	s_lshl_b32 s18, s18, 14
	s_add_i32 s18, s18, s19
	s_add_u32 s0, s72, 0x14a84000
	s_addc_u32 s1, s73, 0
	s_add_u32 s0, s0, s18
	s_addc_u32 s1, s1, 0
	global_load_dwordx4 v[184:187], v145, s[0:1]
	global_load_dwordx4 v[188:191], v145, s[0:1] offset:16
	global_load_dwordx4 v[192:195], v145, s[0:1] offset:32
	global_load_dwordx4 v[196:199], v145, s[0:1] offset:48
	s_lshl_b32 s18, s14, 7
	s_add_i32 s18, s18, s15
	s_lshl_b32 s18, s18, 14
	s_add_u32 s0, s72, 0x10880000
	s_addc_u32 s1, s73, 0
	s_add_u32 s0, s0, s18
	s_addc_u32 s1, s1, 0
	s_add_u32 s2, s72, 0x12880000
	s_addc_u32 s3, s73, 0
	s_add_u32 s2, s2, s18
	s_addc_u32 s3, s3, 0
	s_add_u32 s2, s2, s19
	s_addc_u32 s3, s3, 0
	s_waitcnt vmcnt(0)
	v_mov_b32_e32 v128, v184
	v_mov_b32_e32 v129, v188
	v_mov_b32_e32 v130, v192
	v_mov_b32_e32 v131, v196
	v_mov_b32_e32 v132, v185
	v_mov_b32_e32 v133, v189
	v_mov_b32_e32 v134, v193
	v_mov_b32_e32 v135, v197
	v_mov_b32_e32 v136, v186
	v_mov_b32_e32 v137, v190
	v_mov_b32_e32 v138, v194
	v_mov_b32_e32 v139, v198
	v_mov_b32_e32 v140, v187
	v_mov_b32_e32 v141, v191
	v_mov_b32_e32 v142, v195
	v_mov_b32_e32 v143, v199
	global_load_dwordx4 v[0:3], v144, s[0:1]
	global_load_dwordx4 v[4:7], v144, s[0:1] offset:256
	global_load_dwordx4 v[8:11], v144, s[0:1] offset:512
	global_load_dwordx4 v[12:15], v144, s[0:1] offset:768
	global_load_dwordx4 v[16:19], v144, s[0:1] offset:1024
	global_load_dwordx4 v[20:23], v144, s[0:1] offset:1280
	global_load_dwordx4 v[24:27], v144, s[0:1] offset:1536
	global_load_dwordx4 v[28:31], v144, s[0:1] offset:1792
	global_load_dwordx4 v[32:35], v144, s[0:1] offset:2048
	global_load_dwordx4 v[36:39], v144, s[0:1] offset:2304
	global_load_dwordx4 v[40:43], v144, s[0:1] offset:2560
	global_load_dwordx4 v[44:47], v144, s[0:1] offset:2816
	global_load_dwordx4 v[48:51], v144, s[0:1] offset:3072
	global_load_dwordx4 v[52:55], v144, s[0:1] offset:3328
	global_load_dwordx4 v[56:59], v144, s[0:1] offset:3584
	global_load_dwordx4 v[60:63], v144, s[0:1] offset:3840
	global_load_dwordx4 v[184:187], v145, s[2:3]
	global_load_dwordx4 v[188:191], v145, s[2:3] offset:16
	global_load_dwordx4 v[192:195], v145, s[2:3] offset:32
	global_load_dwordx4 v[196:199], v145, s[2:3] offset:48
	s_mov_b32 s9, 0
.Lp2_l2_loop:
	s_mov_b32 s10, 0x20000
	s_add_u32 s4, s0, s10
	s_addc_u32 s5, s1, 0
	s_add_u32 s6, s2, s10
	s_addc_u32 s7, s3, 0
	global_load_dwordx4 v[64:67], v144, s[4:5]
	global_load_dwordx4 v[68:71], v144, s[4:5] offset:256
	global_load_dwordx4 v[72:75], v144, s[4:5] offset:512
	global_load_dwordx4 v[76:79], v144, s[4:5] offset:768
	global_load_dwordx4 v[80:83], v144, s[4:5] offset:1024
	global_load_dwordx4 v[84:87], v144, s[4:5] offset:1280
	global_load_dwordx4 v[88:91], v144, s[4:5] offset:1536
	global_load_dwordx4 v[92:95], v144, s[4:5] offset:1792
	global_load_dwordx4 v[96:99], v144, s[4:5] offset:2048
	global_load_dwordx4 v[100:103], v144, s[4:5] offset:2304
	global_load_dwordx4 v[104:107], v144, s[4:5] offset:2560
	global_load_dwordx4 v[108:111], v144, s[4:5] offset:2816
	global_load_dwordx4 v[112:115], v144, s[4:5] offset:3072
	global_load_dwordx4 v[116:119], v144, s[4:5] offset:3328
	global_load_dwordx4 v[120:123], v144, s[4:5] offset:3584
	global_load_dwordx4 v[124:127], v144, s[4:5] offset:3840
	global_load_dwordx4 v[200:203], v145, s[6:7]
	global_load_dwordx4 v[204:207], v145, s[6:7] offset:16
	global_load_dwordx4 v[212:215], v145, s[6:7] offset:32
	global_load_dwordx4 v[230:233], v145, s[6:7] offset:48
	v_mov_b32_e32 v234, v128
	v_mov_b32_e32 v235, v132
	v_mov_b32_e32 v236, v136
	v_mov_b32_e32 v237, v140
	global_store_dwordx4 v145, v[234:237], s[2:3]
	v_mov_b32_e32 v238, v129
	v_mov_b32_e32 v239, v133
	v_mov_b32_e32 v240, v137
	v_mov_b32_e32 v241, v141
	global_store_dwordx4 v145, v[238:241], s[2:3] offset:16
	v_mov_b32_e32 v234, v130
	v_mov_b32_e32 v235, v134
	v_mov_b32_e32 v236, v138
	v_mov_b32_e32 v237, v142
	global_store_dwordx4 v145, v[234:237], s[2:3] offset:32
	v_mov_b32_e32 v238, v131
	v_mov_b32_e32 v239, v135
	v_mov_b32_e32 v240, v139
	v_mov_b32_e32 v241, v143
	global_store_dwordx4 v145, v[238:241], s[2:3] offset:48
	s_waitcnt vmcnt(24)
; template <bool HAS_C, bool STORE_STEPS>
; __device__ __forceinline__ void chain16(f32x4 (&acc)[4], const float* Mb, size_t mstride, float* Cb, size_t cstride, int nsteps) {
;     ...
;     for (int c = 0; c < nsteps; ++c) {
;         float* cp = Cb + (size_t)c * cstride;
;         f32x4 q[4];
;         if (HAS_C) {
; #pragma unroll
;             for (int j = 0; j < 4; ++j) q[j] = qn[j];
;             const float* cn = Cb + (size_t)(c + 1 < nsteps ? c + 1 : c) * cstride;
; #pragma unroll
;             for (int j = 0; j < 4; ++j) qn[j] = *(const f32x4*)(cn + 4 * j);
;         }
;         f32x4 mn[16];
;         const float* Mn = Mb + (size_t)(c + 1 < nsteps ? c + 1 : c) * mstride;
; #pragma unroll
;         for (int i = 0; i < 16; ++i) mn[i] = *(const f32x4*)(Mn + (size_t)i * 64);
;         if (STORE_STEPS) {
; #pragma unroll
;             for (int j = 0; j < 4; ++j) *(f32x4*)(cp + 4 * j) = (f32x4){acc[0][j], acc[1][j], acc[2][j], acc[3][j]};
;         }
;         f32x4 na[4];
; #pragma unroll
;         for (int n = 0; n < 4; ++n) na[n] = HAS_C ? (f32x4){q[0][n], q[1][n], q[2][n], q[3][n]} : (f32x4){0.f, 0.f, 0.f, 0.f};
; #pragma unroll
;         for (int n = 0; n < 4; ++n)
; #pragma unroll
;             for (int j = 0; j < 4; ++j) {
;                 const f32x4 a4 = mc[4 * j + n];
; #pragma unroll
;                 for (int np = 0; np < 4; ++np) na[np] = __builtin_amdgcn_mfma_f32_16x16x4f32(a4[np], acc[n][j], na[np], 0, 0, 0);
;             }
; #pragma unroll
;         for (int n = 0; n < 4; ++n) acc[n] = na[n];
; #pragma unroll
;         for (int i = 0; i < 16; ++i) mc[i] = mn[i];
;     }
; __device__ __forceinline__ void stage_rwkv_pass2(const Params& P, int level) {
;     ...
;         for (int it0 = spread ? (wave < 2 ? (int)blockIdx.x : P2_NG * 32) : gw; it0 < P2_NG * 8 * 4; it0 += spread ? P2_NG * 32 : ngw) {
;             int it = it0;
;             if (spread) { const int x = blockIdx.x & 7, j = blockIdx.x >> 3, idx = wave * 32 + j; it = ((idx >> 2) * 8 + x) * 4 + (idx & 3); }
;             const int g = it >> 5, h = (it >> 2) & 7, s = it & 3, v = 16 * s + rho;
;             const float* sg = CG + ((size_t)g * 8 + h) * 4096 + (size_t)v * 64 + 16 * g4;
;             f32x4 q[4];
; #pragma unroll
;             for (int j = 0; j < 4; ++j) q[j] = *(const f32x4*)(sg + 4 * j);
; #pragma unroll
	v_mov_b32_e32 v168, v184
	v_mov_b32_e32 v169, v188
	v_mov_b32_e32 v170, v192
	v_mov_b32_e32 v171, v196
	v_mov_b32_e32 v172, v185
	v_mov_b32_e32 v173, v189
	v_mov_b32_e32 v174, v193
	v_mov_b32_e32 v175, v197
	v_mov_b32_e32 v176, v186
	v_mov_b32_e32 v177, v190
	v_mov_b32_e32 v178, v194
	v_mov_b32_e32 v179, v198
	v_mov_b32_e32 v180, v187
	v_mov_b32_e32 v181, v191
	v_mov_b32_e32 v182, v195
	v_mov_b32_e32 v183, v199
	v_mfma_f32_16x16x4_f32 v[168:171], v0, v128, v[168:171]
	v_mfma_f32_16x16x4_f32 v[172:175], v1, v128, v[172:175]
	v_mfma_f32_16x16x4_f32 v[176:179], v2, v128, v[176:179]
	v_mfma_f32_16x16x4_f32 v[180:183], v3, v128, v[180:183]
	v_mfma_f32_16x16x4_f32 v[168:171], v16, v129, v[168:171]
	v_mfma_f32_16x16x4_f32 v[172:175], v17, v129, v[172:175]
	v_mfma_f32_16x16x4_f32 v[176:179], v18, v129, v[176:179]
	v_mfma_f32_16x16x4_f32 v[180:183], v19, v129, v[180:183]
	v_mfma_f32_16x16x4_f32 v[168:171], v32, v130, v[168:171]
	v_mfma_f32_16x16x4_f32 v[172:175], v33, v130, v[172:175]
	v_mfma_f32_16x16x4_f32 v[176:179], v34, v130, v[176:179]
	v_mfma_f32_16x16x4_f32 v[180:183], v35, v130, v[180:183]
	v_mfma_f32_16x16x4_f32 v[168:171], v48, v131, v[168:171]
	v_mfma_f32_16x16x4_f32 v[172:175], v49, v131, v[172:175]
	v_mfma_f32_16x16x4_f32 v[176:179], v50, v131, v[176:179]
	v_mfma_f32_16x16x4_f32 v[180:183], v51, v131, v[180:183]
	v_mfma_f32_16x16x4_f32 v[168:171], v4, v132, v[168:171]
	v_mfma_f32_16x16x4_f32 v[172:175], v5, v132, v[172:175]
	v_mfma_f32_16x16x4_f32 v[176:179], v6, v132, v[176:179]
	v_mfma_f32_16x16x4_f32 v[180:183], v7, v132, v[180:183]
	v_mfma_f32_16x16x4_f32 v[168:171], v20, v133, v[168:171]
	v_mfma_f32_16x16x4_f32 v[172:175], v21, v133, v[172:175]
	v_mfma_f32_16x16x4_f32 v[176:179], v22, v133, v[176:179]
	v_mfma_f32_16x16x4_f32 v[180:183], v23, v133, v[180:183]
	v_mfma_f32_16x16x4_f32 v[168:171], v36, v134, v[168:171]
	v_mfma_f32_16x16x4_f32 v[172:175], v37, v134, v[172:175]
	v_mfma_f32_16x16x4_f32 v[176:179], v38, v134, v[176:179]
	v_mfma_f32_16x16x4_f32 v[180:183], v39, v134, v[180:183]
	v_mfma_f32_16x16x4_f32 v[168:171], v52, v135, v[168:171]
	v_mfma_f32_16x16x4_f32 v[172:175], v53, v135, v[172:175]
	v_mfma_f32_16x16x4_f32 v[176:179], v54, v135, v[176:179]
	v_mfma_f32_16x16x4_f32 v[180:183], v55, v135, v[180:183]
	v_mfma_f32_16x16x4_f32 v[168:171], v8, v136, v[168:171]
	v_mfma_f32_16x16x4_f32 v[172:175], v9, v136, v[172:175]
	v_mfma_f32_16x16x4_f32 v[176:179], v10, v136, v[176:179]
	v_mfma_f32_16x16x4_f32 v[180:183], v11, v136, v[180:183]
	v_mfma_f32_16x16x4_f32 v[168:171], v24, v137, v[168:171]
	v_mfma_f32_16x16x4_f32 v[172:175], v25, v137, v[172:175]
	v_mfma_f32_16x16x4_f32 v[176:179], v26, v137, v[176:179]
	v_mfma_f32_16x16x4_f32 v[180:183], v27, v137, v[180:183]
	v_mfma_f32_16x16x4_f32 v[168:171], v40, v138, v[168:171]
	v_mfma_f32_16x16x4_f32 v[172:175], v41, v138, v[172:175]
	v_mfma_f32_16x16x4_f32 v[176:179], v42, v138, v[176:179]
	v_mfma_f32_16x16x4_f32 v[180:183], v43, v138, v[180:183]
	v_mfma_f32_16x16x4_f32 v[168:171], v56, v139, v[168:171]
	v_mfma_f32_16x16x4_f32 v[172:175], v57, v139, v[172:175]
	v_mfma_f32_16x16x4_f32 v[176:179], v58, v139, v[176:179]
	v_mfma_f32_16x16x4_f32 v[180:183], v59, v139, v[180:183]
	v_mfma_f32_16x16x4_f32 v[168:171], v12, v140, v[168:171]
	v_mfma_f32_16x16x4_f32 v[172:175], v13, v140, v[172:175]
	v_mfma_f32_16x16x4_f32 v[176:179], v14, v140, v[176:179]
	v_mfma_f32_16x16x4_f32 v[180:183], v15, v140, v[180:183]
	v_mfma_f32_16x16x4_f32 v[168:171], v28, v141, v[168:171]
	v_mfma_f32_16x16x4_f32 v[172:175], v29, v141, v[172:175]
	v_mfma_f32_16x16x4_f32 v[176:179], v30, v141, v[176:179]
	v_mfma_f32_16x16x4_f32 v[180:183], v31, v141, v[180:183]
	v_mfma_f32_16x16x4_f32 v[168:171], v44, v142, v[168:171]
	v_mfma_f32_16x16x4_f32 v[172:175], v45, v142, v[172:175]
	v_mfma_f32_16x16x4_f32 v[176:179], v46, v142, v[176:179]
	v_mfma_f32_16x16x4_f32 v[180:183], v47, v142, v[180:183]
	v_mfma_f32_16x16x4_f32 v[168:171], v60, v143, v[168:171]
	v_mfma_f32_16x16x4_f32 v[172:175], v61, v143, v[172:175]
	v_mfma_f32_16x16x4_f32 v[176:179], v62, v143, v[176:179]
	v_mfma_f32_16x16x4_f32 v[180:183], v63, v143, v[180:183]
	s_mov_b64 s[0:1], s[4:5]
	s_mov_b64 s[2:3], s[6:7]
	s_cmp_eq_u32 s9, 7
	s_cselect_b32 s10, 0, 0x20000
	s_add_u32 s4, s0, s10
	s_addc_u32 s5, s1, 0
	s_add_u32 s6, s2, s10
	s_addc_u32 s7, s3, 0
	global_load_dwordx4 v[0:3], v144, s[4:5]
	global_load_dwordx4 v[4:7], v144, s[4:5] offset:256
	global_load_dwordx4 v[8:11], v144, s[4:5] offset:512
	global_load_dwordx4 v[12:15], v144, s[4:5] offset:768
	global_load_dwordx4 v[16:19], v144, s[4:5] offset:1024
	global_load_dwordx4 v[20:23], v144, s[4:5] offset:1280
	global_load_dwordx4 v[24:27], v144, s[4:5] offset:1536
	global_load_dwordx4 v[28:31], v144, s[4:5] offset:1792
	global_load_dwordx4 v[32:35], v144, s[4:5] offset:2048
	global_load_dwordx4 v[36:39], v144, s[4:5] offset:2304
	global_load_dwordx4 v[40:43], v144, s[4:5] offset:2560
	global_load_dwordx4 v[44:47], v144, s[4:5] offset:2816
	global_load_dwordx4 v[48:51], v144, s[4:5] offset:3072
	global_load_dwordx4 v[52:55], v144, s[4:5] offset:3328
	global_load_dwordx4 v[56:59], v144, s[4:5] offset:3584
	global_load_dwordx4 v[60:63], v144, s[4:5] offset:3840
	global_load_dwordx4 v[184:187], v145, s[6:7]
	global_load_dwordx4 v[188:191], v145, s[6:7] offset:16
	global_load_dwordx4 v[192:195], v145, s[6:7] offset:32
	global_load_dwordx4 v[196:199], v145, s[6:7] offset:48
	v_mov_b32_e32 v234, v168
	v_mov_b32_e32 v235, v172
	v_mov_b32_e32 v236, v176
	v_mov_b32_e32 v237, v180
	global_store_dwordx4 v145, v[234:237], s[2:3]
	v_mov_b32_e32 v238, v169
	v_mov_b32_e32 v239, v173
	v_mov_b32_e32 v240, v177
	v_mov_b32_e32 v241, v181
	global_store_dwordx4 v145, v[238:241], s[2:3] offset:16
	v_mov_b32_e32 v234, v170
	v_mov_b32_e32 v235, v174
	v_mov_b32_e32 v236, v178
	v_mov_b32_e32 v237, v182
	global_store_dwordx4 v145, v[234:237], s[2:3] offset:32
	v_mov_b32_e32 v238, v171
	v_mov_b32_e32 v239, v175
	v_mov_b32_e32 v240, v179
	v_mov_b32_e32 v241, v183
	global_store_dwordx4 v145, v[238:241], s[2:3] offset:48
	s_waitcnt vmcnt(24)
; template <bool HAS_C, bool STORE_STEPS>
; __device__ __forceinline__ void chain16(f32x4 (&acc)[4], const float* Mb, size_t mstride, float* Cb, size_t cstride, int nsteps) {
;     ...
;     for (int c = 0; c < nsteps; ++c) {
;         float* cp = Cb + (size_t)c * cstride;
;         f32x4 q[4];
;         if (HAS_C) {
; #pragma unroll
;             for (int j = 0; j < 4; ++j) q[j] = qn[j];
;             const float* cn = Cb + (size_t)(c + 1 < nsteps ? c + 1 : c) * cstride;
; #pragma unroll
;             for (int j = 0; j < 4; ++j) qn[j] = *(const f32x4*)(cn + 4 * j);
;         }
;         f32x4 mn[16];
;         const float* Mn = Mb + (size_t)(c + 1 < nsteps ? c + 1 : c) * mstride;
; #pragma unroll
;         for (int i = 0; i < 16; ++i) mn[i] = *(const f32x4*)(Mn + (size_t)i * 64);
;         if (STORE_STEPS) {
; #pragma unroll
;             for (int j = 0; j < 4; ++j) *(f32x4*)(cp + 4 * j) = (f32x4){acc[0][j], acc[1][j], acc[2][j], acc[3][j]};
;         }
;         f32x4 na[4];
; #pragma unroll
;         for (int n = 0; n < 4; ++n) na[n] = HAS_C ? (f32x4){q[0][n], q[1][n], q[2][n], q[3][n]} : (f32x4){0.f, 0.f, 0.f, 0.f};
; #pragma unroll
;         for (int n = 0; n < 4; ++n)
; #pragma unroll
;             for (int j = 0; j < 4; ++j) {
;                 const f32x4 a4 = mc[4 * j + n];
; #pragma unroll
;                 for (int np = 0; np < 4; ++np) na[np] = __builtin_amdgcn_mfma_f32_16x16x4f32(a4[np], acc[n][j], na[np], 0, 0, 0);
;             }
; #pragma unroll
;         for (int n = 0; n < 4; ++n) acc[n] = na[n];
; #pragma unroll
;         for (int i = 0; i < 16; ++i) mc[i] = mn[i];
;     }
; __device__ __forceinline__ void stage_rwkv_pass2(const Params& P, int level) {
;     ...
;     } else if (level == 1) {
;         if (wave == 0 && blockIdx.x < 32) {
;             const int h = blockIdx.x >> 2, s = blockIdx.x & 3, v = 16 * s + rho;
; #pragma unroll
;             for (int n = 0; n < 4; ++n) acc[n] = (f32x4){0.f, 0.f, 0.f, 0.f};
;             chain16<true, true>(acc, MG + (size_t)h * 4096 + (size_t)(16 * g4) * 64 + 4 * rho, 32768, CG + (size_t)h * 4096 + (size_t)v * 64 + 16 * g4, 32768, P2_NG);
	v_mov_b32_e32 v128, v200
	v_mov_b32_e32 v129, v204
	v_mov_b32_e32 v130, v212
	v_mov_b32_e32 v131, v230
	v_mov_b32_e32 v132, v201
	v_mov_b32_e32 v133, v205
	v_mov_b32_e32 v134, v213
	v_mov_b32_e32 v135, v231
	v_mov_b32_e32 v136, v202
	v_mov_b32_e32 v137, v206
	v_mov_b32_e32 v138, v214
	v_mov_b32_e32 v139, v232
	v_mov_b32_e32 v140, v203
	v_mov_b32_e32 v141, v207
	v_mov_b32_e32 v142, v215
	v_mov_b32_e32 v143, v233
	v_mfma_f32_16x16x4_f32 v[128:131], v64, v168, v[128:131]
	v_mfma_f32_16x16x4_f32 v[132:135], v65, v168, v[132:135]
	v_mfma_f32_16x16x4_f32 v[136:139], v66, v168, v[136:139]
	v_mfma_f32_16x16x4_f32 v[140:143], v67, v168, v[140:143]
	v_mfma_f32_16x16x4_f32 v[128:131], v80, v169, v[128:131]
	v_mfma_f32_16x16x4_f32 v[132:135], v81, v169, v[132:135]
	v_mfma_f32_16x16x4_f32 v[136:139], v82, v169, v[136:139]
	v_mfma_f32_16x16x4_f32 v[140:143], v83, v169, v[140:143]
	v_mfma_f32_16x16x4_f32 v[128:131], v96, v170, v[128:131]
	v_mfma_f32_16x16x4_f32 v[132:135], v97, v170, v[132:135]
	v_mfma_f32_16x16x4_f32 v[136:139], v98, v170, v[136:139]
	v_mfma_f32_16x16x4_f32 v[140:143], v99, v170, v[140:143]
	v_mfma_f32_16x16x4_f32 v[128:131], v112, v171, v[128:131]
	v_mfma_f32_16x16x4_f32 v[132:135], v113, v171, v[132:135]
	v_mfma_f32_16x16x4_f32 v[136:139], v114, v171, v[136:139]
	v_mfma_f32_16x16x4_f32 v[140:143], v115, v171, v[140:143]
	v_mfma_f32_16x16x4_f32 v[128:131], v68, v172, v[128:131]
	v_mfma_f32_16x16x4_f32 v[132:135], v69, v172, v[132:135]
	v_mfma_f32_16x16x4_f32 v[136:139], v70, v172, v[136:139]
	v_mfma_f32_16x16x4_f32 v[140:143], v71, v172, v[140:143]
	v_mfma_f32_16x16x4_f32 v[128:131], v84, v173, v[128:131]
	v_mfma_f32_16x16x4_f32 v[132:135], v85, v173, v[132:135]
	v_mfma_f32_16x16x4_f32 v[136:139], v86, v173, v[136:139]
	v_mfma_f32_16x16x4_f32 v[140:143], v87, v173, v[140:143]
	v_mfma_f32_16x16x4_f32 v[128:131], v100, v174, v[128:131]
	v_mfma_f32_16x16x4_f32 v[132:135], v101, v174, v[132:135]
	v_mfma_f32_16x16x4_f32 v[136:139], v102, v174, v[136:139]
	v_mfma_f32_16x16x4_f32 v[140:143], v103, v174, v[140:143]
	v_mfma_f32_16x16x4_f32 v[128:131], v116, v175, v[128:131]
	v_mfma_f32_16x16x4_f32 v[132:135], v117, v175, v[132:135]
	v_mfma_f32_16x16x4_f32 v[136:139], v118, v175, v[136:139]
	v_mfma_f32_16x16x4_f32 v[140:143], v119, v175, v[140:143]
	v_mfma_f32_16x16x4_f32 v[128:131], v72, v176, v[128:131]
	v_mfma_f32_16x16x4_f32 v[132:135], v73, v176, v[132:135]
	v_mfma_f32_16x16x4_f32 v[136:139], v74, v176, v[136:139]
	v_mfma_f32_16x16x4_f32 v[140:143], v75, v176, v[140:143]
	v_mfma_f32_16x16x4_f32 v[128:131], v88, v177, v[128:131]
	v_mfma_f32_16x16x4_f32 v[132:135], v89, v177, v[132:135]
	v_mfma_f32_16x16x4_f32 v[136:139], v90, v177, v[136:139]
	v_mfma_f32_16x16x4_f32 v[140:143], v91, v177, v[140:143]
	v_mfma_f32_16x16x4_f32 v[128:131], v104, v178, v[128:131]
	v_mfma_f32_16x16x4_f32 v[132:135], v105, v178, v[132:135]
	v_mfma_f32_16x16x4_f32 v[136:139], v106, v178, v[136:139]
	v_mfma_f32_16x16x4_f32 v[140:143], v107, v178, v[140:143]
	v_mfma_f32_16x16x4_f32 v[128:131], v120, v179, v[128:131]
	v_mfma_f32_16x16x4_f32 v[132:135], v121, v179, v[132:135]
	v_mfma_f32_16x16x4_f32 v[136:139], v122, v179, v[136:139]
	v_mfma_f32_16x16x4_f32 v[140:143], v123, v179, v[140:143]
	v_mfma_f32_16x16x4_f32 v[128:131], v76, v180, v[128:131]
	v_mfma_f32_16x16x4_f32 v[132:135], v77, v180, v[132:135]
	v_mfma_f32_16x16x4_f32 v[136:139], v78, v180, v[136:139]
	v_mfma_f32_16x16x4_f32 v[140:143], v79, v180, v[140:143]
	v_mfma_f32_16x16x4_f32 v[128:131], v92, v181, v[128:131]
	v_mfma_f32_16x16x4_f32 v[132:135], v93, v181, v[132:135]
	v_mfma_f32_16x16x4_f32 v[136:139], v94, v181, v[136:139]
	v_mfma_f32_16x16x4_f32 v[140:143], v95, v181, v[140:143]
	v_mfma_f32_16x16x4_f32 v[128:131], v108, v182, v[128:131]
	v_mfma_f32_16x16x4_f32 v[132:135], v109, v182, v[132:135]
	v_mfma_f32_16x16x4_f32 v[136:139], v110, v182, v[136:139]
	v_mfma_f32_16x16x4_f32 v[140:143], v111, v182, v[140:143]
	v_mfma_f32_16x16x4_f32 v[128:131], v124, v183, v[128:131]
	v_mfma_f32_16x16x4_f32 v[132:135], v125, v183, v[132:135]
	v_mfma_f32_16x16x4_f32 v[136:139], v126, v183, v[136:139]
	v_mfma_f32_16x16x4_f32 v[140:143], v127, v183, v[140:143]
	s_mov_b64 s[0:1], s[4:5]
	s_mov_b64 s[2:3], s[6:7]
	s_add_i32 s9, s9, 1
	s_cmp_eq_u32 s9, 8
	s_cbranch_scc0 .Lp2_l2_loop
	s_nop 7
	s_nop 3
	s_add_i32 s8, s8, s16
	s_cmpk_gt_i32 s8, 0x1ff
	s_cbranch_scc0 .Lp2l2_item
.Lp2l2_end:
.LBB0_220:
	s_mov_b64 s[0:1], 0
.LBB0_221:
	s_andn2_b64 vcc, exec, s[0:1]
	s_cbranch_vccnz .LBB0_253
	s_cmp_gt_i32 s67, 9
	s_mov_b64 s[0:1], -1
	s_cbranch_scc0 .LBB0_228
	v_readfirstlane_b32 s0, v211
	s_lshr_b32 s11, s0, 6
	s_cmp_lg_u32 s11, 0
	s_cbranch_scc1 .Lp2l1_end
	s_cmp_gt_u32 s54, 31
	s_cbranch_scc1 .Lp2l1_end
	v_and_b32_e32 v146, 63, v211
	v_and_b32_e32 v147, 15, v146
	v_lshrrev_b32_e32 v148, 4, v146
	v_lshlrev_b32_e32 v144, 12, v148
	v_lshl_add_u32 v144, v147, 4, v144
	v_lshlrev_b32_e32 v145, 6, v148
	v_lshl_add_u32 v145, v147, 8, v145
	s_lshr_b32 s15, s54, 2
	s_and_b32 s17, s54, 3
	s_lshl_b32 s18, s15, 14
	s_lshl_b32 s19, s17, 12
	s_add_u32 s0, s72, 0x14884000
	s_addc_u32 s1, s73, 0
	s_add_u32 s0, s0, s18
	s_addc_u32 s1, s1, 0
	s_add_u32 s2, s72, 0x14a84000
	s_addc_u32 s3, s73, 0
	s_add_u32 s2, s2, s18
	s_addc_u32 s3, s3, 0
	s_add_u32 s2, s2, s19
	s_addc_u32 s3, s3, 0
	v_mov_b32_e32 v128, 0
	v_mov_b32_e32 v129, 0
	v_mov_b32_e32 v130, 0
	v_mov_b32_e32 v131, 0
	v_mov_b32_e32 v132, 0
	v_mov_b32_e32 v133, 0
	v_mov_b32_e32 v134, 0
	v_mov_b32_e32 v135, 0
	v_mov_b32_e32 v136, 0
	v_mov_b32_e32 v137, 0
	v_mov_b32_e32 v138, 0
	v_mov_b32_e32 v139, 0
	v_mov_b32_e32 v140, 0
	v_mov_b32_e32 v141, 0
	v_mov_b32_e32 v142, 0
	v_mov_b32_e32 v143, 0
	global_load_dwordx4 v[0:3], v144, s[0:1]
	global_load_dwordx4 v[4:7], v144, s[0:1] offset:256
	global_load_dwordx4 v[8:11], v144, s[0:1] offset:512
	global_load_dwordx4 v[12:15], v144, s[0:1] offset:768
	global_load_dwordx4 v[16:19], v144, s[0:1] offset:1024
	global_load_dwordx4 v[20:23], v144, s[0:1] offset:1280
	global_load_dwordx4 v[24:27], v144, s[0:1] offset:1536
	global_load_dwordx4 v[28:31], v144, s[0:1] offset:1792
	global_load_dwordx4 v[32:35], v144, s[0:1] offset:2048
	global_load_dwordx4 v[36:39], v144, s[0:1] offset:2304
	global_load_dwordx4 v[40:43], v144, s[0:1] offset:2560
	global_load_dwordx4 v[44:47], v144, s[0:1] offset:2816
	global_load_dwordx4 v[48:51], v144, s[0:1] offset:3072
	global_load_dwordx4 v[52:55], v144, s[0:1] offset:3328
	global_load_dwordx4 v[56:59], v144, s[0:1] offset:3584
	global_load_dwordx4 v[60:63], v144, s[0:1] offset:3840
	global_load_dwordx4 v[184:187], v145, s[2:3]
	global_load_dwordx4 v[188:191], v145, s[2:3] offset:16
	global_load_dwordx4 v[192:195], v145, s[2:3] offset:32
	global_load_dwordx4 v[196:199], v145, s[2:3] offset:48
	s_mov_b32 s9, 0
; template <bool HAS_C, bool STORE_STEPS>
; __device__ __forceinline__ void chain16(f32x4 (&acc)[4], const float* Mb, size_t mstride, float* Cb, size_t cstride, int nsteps) {
;     ...
;     for (int c = 0; c < nsteps; ++c) {
;         float* cp = Cb + (size_t)c * cstride;
;         f32x4 q[4];
;         if (HAS_C) {
; #pragma unroll
;             for (int j = 0; j < 4; ++j) q[j] = qn[j];
;             const float* cn = Cb + (size_t)(c + 1 < nsteps ? c + 1 : c) * cstride;
; #pragma unroll
;             for (int j = 0; j < 4; ++j) qn[j] = *(const f32x4*)(cn + 4 * j);
;         }
;         f32x4 mn[16];
;         const float* Mn = Mb + (size_t)(c + 1 < nsteps ? c + 1 : c) * mstride;
; #pragma unroll
;         for (int i = 0; i < 16; ++i) mn[i] = *(const f32x4*)(Mn + (size_t)i * 64);
;         if (STORE_STEPS) {
; #pragma unroll
;             for (int j = 0; j < 4; ++j) *(f32x4*)(cp + 4 * j) = (f32x4){acc[0][j], acc[1][j], acc[2][j], acc[3][j]};
;         }
;         f32x4 na[4];
; #pragma unroll
;         for (int n = 0; n < 4; ++n) na[n] = HAS_C ? (f32x4){q[0][n], q[1][n], q[2][n], q[3][n]} : (f32x4){0.f, 0.f, 0.f, 0.f};
; #pragma unroll
;         for (int n = 0; n < 4; ++n)
; #pragma unroll
;             for (int j = 0; j < 4; ++j) {
;                 const f32x4 a4 = mc[4 * j + n];
; #pragma unroll
;                 for (int np = 0; np < 4; ++np) na[np] = __builtin_amdgcn_mfma_f32_16x16x4f32(a4[np], acc[n][j], na[np], 0, 0, 0);
;             }
; #pragma unroll
;         for (int n = 0; n < 4; ++n) acc[n] = na[n];
; #pragma unroll
;         for (int i = 0; i < 16; ++i) mc[i] = mn[i];
;     }
; __device__ __forceinline__ void stage_rwkv_pass2(const Params& P, int level) {
;     ...
;         if (wave == 0 && blockIdx.x < 32) {
;             const int h = blockIdx.x >> 2, s = blockIdx.x & 3, v = 16 * s + rho;
; #pragma unroll
;             for (int n = 0; n < 4; ++n) acc[n] = (f32x4){0.f, 0.f, 0.f, 0.f};
;             chain16<true, true>(acc, MG + (size_t)h * 4096 + (size_t)(16 * g4) * 64 + 4 * rho, 32768, CG + (size_t)h * 4096 + (size_t)v * 64 + 16 * g4, 32768, P2_NG);
.Lp2_l1_loop:
	s_mov_b32 s10, 0x20000
	s_add_u32 s4, s0, s10
	s_addc_u32 s5, s1, 0
	s_add_u32 s6, s2, s10
	s_addc_u32 s7, s3, 0
	global_load_dwordx4 v[64:67], v144, s[4:5]
	global_load_dwordx4 v[68:71], v144, s[4:5] offset:256
	global_load_dwordx4 v[72:75], v144, s[4:5] offset:512
	global_load_dwordx4 v[76:79], v144, s[4:5] offset:768
	global_load_dwordx4 v[80:83], v144, s[4:5] offset:1024
	global_load_dwordx4 v[84:87], v144, s[4:5] offset:1280
	global_load_dwordx4 v[88:91], v144, s[4:5] offset:1536
	global_load_dwordx4 v[92:95], v144, s[4:5] offset:1792
	global_load_dwordx4 v[96:99], v144, s[4:5] offset:2048
	global_load_dwordx4 v[100:103], v144, s[4:5] offset:2304
	global_load_dwordx4 v[104:107], v144, s[4:5] offset:2560
	global_load_dwordx4 v[108:111], v144, s[4:5] offset:2816
	global_load_dwordx4 v[112:115], v144, s[4:5] offset:3072
	global_load_dwordx4 v[116:119], v144, s[4:5] offset:3328
	global_load_dwordx4 v[120:123], v144, s[4:5] offset:3584
	global_load_dwordx4 v[124:127], v144, s[4:5] offset:3840
	global_load_dwordx4 v[200:203], v145, s[6:7]
	global_load_dwordx4 v[204:207], v145, s[6:7] offset:16
	global_load_dwordx4 v[212:215], v145, s[6:7] offset:32
	global_load_dwordx4 v[230:233], v145, s[6:7] offset:48
	v_mov_b32_e32 v234, v128
	v_mov_b32_e32 v235, v132
	v_mov_b32_e32 v236, v136
	v_mov_b32_e32 v237, v140
	global_store_dwordx4 v145, v[234:237], s[2:3]
	v_mov_b32_e32 v238, v129
	v_mov_b32_e32 v239, v133
	v_mov_b32_e32 v240, v137
	v_mov_b32_e32 v241, v141
	global_store_dwordx4 v145, v[238:241], s[2:3] offset:16
	v_mov_b32_e32 v234, v130
	v_mov_b32_e32 v235, v134
	v_mov_b32_e32 v236, v138
	v_mov_b32_e32 v237, v142
	global_store_dwordx4 v145, v[234:237], s[2:3] offset:32
	v_mov_b32_e32 v238, v131
	v_mov_b32_e32 v239, v135
	v_mov_b32_e32 v240, v139
	v_mov_b32_e32 v241, v143
	global_store_dwordx4 v145, v[238:241], s[2:3] offset:48
	s_waitcnt vmcnt(24)
	v_mov_b32_e32 v168, v184
	v_mov_b32_e32 v169, v188
	v_mov_b32_e32 v170, v192
	v_mov_b32_e32 v171, v196
	v_mov_b32_e32 v172, v185
	v_mov_b32_e32 v173, v189
	v_mov_b32_e32 v174, v193
	v_mov_b32_e32 v175, v197
	v_mov_b32_e32 v176, v186
	v_mov_b32_e32 v177, v190
	v_mov_b32_e32 v178, v194
	v_mov_b32_e32 v179, v198
	v_mov_b32_e32 v180, v187
	v_mov_b32_e32 v181, v191
	v_mov_b32_e32 v182, v195
	v_mov_b32_e32 v183, v199
	v_mfma_f32_16x16x4_f32 v[168:171], v0, v128, v[168:171]
	v_mfma_f32_16x16x4_f32 v[172:175], v1, v128, v[172:175]
	v_mfma_f32_16x16x4_f32 v[176:179], v2, v128, v[176:179]
	v_mfma_f32_16x16x4_f32 v[180:183], v3, v128, v[180:183]
	v_mfma_f32_16x16x4_f32 v[168:171], v16, v129, v[168:171]
	v_mfma_f32_16x16x4_f32 v[172:175], v17, v129, v[172:175]
	v_mfma_f32_16x16x4_f32 v[176:179], v18, v129, v[176:179]
	v_mfma_f32_16x16x4_f32 v[180:183], v19, v129, v[180:183]
	v_mfma_f32_16x16x4_f32 v[168:171], v32, v130, v[168:171]
	v_mfma_f32_16x16x4_f32 v[172:175], v33, v130, v[172:175]
	v_mfma_f32_16x16x4_f32 v[176:179], v34, v130, v[176:179]
	v_mfma_f32_16x16x4_f32 v[180:183], v35, v130, v[180:183]
	v_mfma_f32_16x16x4_f32 v[168:171], v48, v131, v[168:171]
	v_mfma_f32_16x16x4_f32 v[172:175], v49, v131, v[172:175]
	v_mfma_f32_16x16x4_f32 v[176:179], v50, v131, v[176:179]
	v_mfma_f32_16x16x4_f32 v[180:183], v51, v131, v[180:183]
	v_mfma_f32_16x16x4_f32 v[168:171], v4, v132, v[168:171]
	v_mfma_f32_16x16x4_f32 v[172:175], v5, v132, v[172:175]
	v_mfma_f32_16x16x4_f32 v[176:179], v6, v132, v[176:179]
	v_mfma_f32_16x16x4_f32 v[180:183], v7, v132, v[180:183]
	v_mfma_f32_16x16x4_f32 v[168:171], v20, v133, v[168:171]
	v_mfma_f32_16x16x4_f32 v[172:175], v21, v133, v[172:175]
	v_mfma_f32_16x16x4_f32 v[176:179], v22, v133, v[176:179]
	v_mfma_f32_16x16x4_f32 v[180:183], v23, v133, v[180:183]
	v_mfma_f32_16x16x4_f32 v[168:171], v36, v134, v[168:171]
	v_mfma_f32_16x16x4_f32 v[172:175], v37, v134, v[172:175]
	v_mfma_f32_16x16x4_f32 v[176:179], v38, v134, v[176:179]
	v_mfma_f32_16x16x4_f32 v[180:183], v39, v134, v[180:183]
	v_mfma_f32_16x16x4_f32 v[168:171], v52, v135, v[168:171]
	v_mfma_f32_16x16x4_f32 v[172:175], v53, v135, v[172:175]
	v_mfma_f32_16x16x4_f32 v[176:179], v54, v135, v[176:179]
	v_mfma_f32_16x16x4_f32 v[180:183], v55, v135, v[180:183]
	v_mfma_f32_16x16x4_f32 v[168:171], v8, v136, v[168:171]
	v_mfma_f32_16x16x4_f32 v[172:175], v9, v136, v[172:175]
	v_mfma_f32_16x16x4_f32 v[176:179], v10, v136, v[176:179]
	v_mfma_f32_16x16x4_f32 v[180:183], v11, v136, v[180:183]
	v_mfma_f32_16x16x4_f32 v[168:171], v24, v137, v[168:171]
	v_mfma_f32_16x16x4_f32 v[172:175], v25, v137, v[172:175]
	v_mfma_f32_16x16x4_f32 v[176:179], v26, v137, v[176:179]
	v_mfma_f32_16x16x4_f32 v[180:183], v27, v137, v[180:183]
	v_mfma_f32_16x16x4_f32 v[168:171], v40, v138, v[168:171]
	v_mfma_f32_16x16x4_f32 v[172:175], v41, v138, v[172:175]
	v_mfma_f32_16x16x4_f32 v[176:179], v42, v138, v[176:179]
	v_mfma_f32_16x16x4_f32 v[180:183], v43, v138, v[180:183]
	v_mfma_f32_16x16x4_f32 v[168:171], v56, v139, v[168:171]
	v_mfma_f32_16x16x4_f32 v[172:175], v57, v139, v[172:175]
	v_mfma_f32_16x16x4_f32 v[176:179], v58, v139, v[176:179]
	v_mfma_f32_16x16x4_f32 v[180:183], v59, v139, v[180:183]
	v_mfma_f32_16x16x4_f32 v[168:171], v12, v140, v[168:171]
	v_mfma_f32_16x16x4_f32 v[172:175], v13, v140, v[172:175]
	v_mfma_f32_16x16x4_f32 v[176:179], v14, v140, v[176:179]
	v_mfma_f32_16x16x4_f32 v[180:183], v15, v140, v[180:183]
	v_mfma_f32_16x16x4_f32 v[168:171], v28, v141, v[168:171]
	v_mfma_f32_16x16x4_f32 v[172:175], v29, v141, v[172:175]
	v_mfma_f32_16x16x4_f32 v[176:179], v30, v141, v[176:179]
	v_mfma_f32_16x16x4_f32 v[180:183], v31, v141, v[180:183]
	v_mfma_f32_16x16x4_f32 v[168:171], v44, v142, v[168:171]
	v_mfma_f32_16x16x4_f32 v[172:175], v45, v142, v[172:175]
; template <bool HAS_C, bool STORE_STEPS>
; __device__ __forceinline__ void chain16(f32x4 (&acc)[4], const float* Mb, size_t mstride, float* Cb, size_t cstride, int nsteps) {
;     ...
;     for (int c = 0; c < nsteps; ++c) {
;         float* cp = Cb + (size_t)c * cstride;
;         f32x4 q[4];
;         if (HAS_C) {
; #pragma unroll
;             for (int j = 0; j < 4; ++j) q[j] = qn[j];
;             const float* cn = Cb + (size_t)(c + 1 < nsteps ? c + 1 : c) * cstride;
; #pragma unroll
;             for (int j = 0; j < 4; ++j) qn[j] = *(const f32x4*)(cn + 4 * j);
;         }
;         f32x4 mn[16];
;         const float* Mn = Mb + (size_t)(c + 1 < nsteps ? c + 1 : c) * mstride;
; #pragma unroll
;         for (int i = 0; i < 16; ++i) mn[i] = *(const f32x4*)(Mn + (size_t)i * 64);
;         if (STORE_STEPS) {
; #pragma unroll
;             for (int j = 0; j < 4; ++j) *(f32x4*)(cp + 4 * j) = (f32x4){acc[0][j], acc[1][j], acc[2][j], acc[3][j]};
;         }
;         f32x4 na[4];
; #pragma unroll
;         for (int n = 0; n < 4; ++n) na[n] = HAS_C ? (f32x4){q[0][n], q[1][n], q[2][n], q[3][n]} : (f32x4){0.f, 0.f, 0.f, 0.f};
; #pragma unroll
;         for (int n = 0; n < 4; ++n)
; #pragma unroll
;             for (int j = 0; j < 4; ++j) {
;                 const f32x4 a4 = mc[4 * j + n];
; #pragma unroll
;                 for (int np = 0; np < 4; ++np) na[np] = __builtin_amdgcn_mfma_f32_16x16x4f32(a4[np], acc[n][j], na[np], 0, 0, 0);
;             }
; #pragma unroll
;         for (int n = 0; n < 4; ++n) acc[n] = na[n];
; #pragma unroll
;         for (int i = 0; i < 16; ++i) mc[i] = mn[i];
;     }
	v_mfma_f32_16x16x4_f32 v[176:179], v46, v142, v[176:179]
	v_mfma_f32_16x16x4_f32 v[180:183], v47, v142, v[180:183]
	v_mfma_f32_16x16x4_f32 v[168:171], v60, v143, v[168:171]
	v_mfma_f32_16x16x4_f32 v[172:175], v61, v143, v[172:175]
	v_mfma_f32_16x16x4_f32 v[176:179], v62, v143, v[176:179]
	v_mfma_f32_16x16x4_f32 v[180:183], v63, v143, v[180:183]
	s_mov_b64 s[0:1], s[4:5]
	s_mov_b64 s[2:3], s[6:7]
	s_cmp_eq_u32 s9, 7
	s_cselect_b32 s10, 0, 0x20000
	s_add_u32 s4, s0, s10
	s_addc_u32 s5, s1, 0
	s_add_u32 s6, s2, s10
	s_addc_u32 s7, s3, 0
	global_load_dwordx4 v[0:3], v144, s[4:5]
	global_load_dwordx4 v[4:7], v144, s[4:5] offset:256
	global_load_dwordx4 v[8:11], v144, s[4:5] offset:512
	global_load_dwordx4 v[12:15], v144, s[4:5] offset:768
	global_load_dwordx4 v[16:19], v144, s[4:5] offset:1024
	global_load_dwordx4 v[20:23], v144, s[4:5] offset:1280
	global_load_dwordx4 v[24:27], v144, s[4:5] offset:1536
	global_load_dwordx4 v[28:31], v144, s[4:5] offset:1792
	global_load_dwordx4 v[32:35], v144, s[4:5] offset:2048
	global_load_dwordx4 v[36:39], v144, s[4:5] offset:2304
	global_load_dwordx4 v[40:43], v144, s[4:5] offset:2560
	global_load_dwordx4 v[44:47], v144, s[4:5] offset:2816
	global_load_dwordx4 v[48:51], v144, s[4:5] offset:3072
	global_load_dwordx4 v[52:55], v144, s[4:5] offset:3328
	global_load_dwordx4 v[56:59], v144, s[4:5] offset:3584
	global_load_dwordx4 v[60:63], v144, s[4:5] offset:3840
	global_load_dwordx4 v[184:187], v145, s[6:7]
	global_load_dwordx4 v[188:191], v145, s[6:7] offset:16
	global_load_dwordx4 v[192:195], v145, s[6:7] offset:32
	global_load_dwordx4 v[196:199], v145, s[6:7] offset:48
	v_mov_b32_e32 v234, v168
	v_mov_b32_e32 v235, v172
	v_mov_b32_e32 v236, v176
	v_mov_b32_e32 v237, v180
	global_store_dwordx4 v145, v[234:237], s[2:3]
	v_mov_b32_e32 v238, v169
	v_mov_b32_e32 v239, v173
	v_mov_b32_e32 v240, v177
	v_mov_b32_e32 v241, v181
	global_store_dwordx4 v145, v[238:241], s[2:3] offset:16
	v_mov_b32_e32 v234, v170
	v_mov_b32_e32 v235, v174
	v_mov_b32_e32 v236, v178
	v_mov_b32_e32 v237, v182
	global_store_dwordx4 v145, v[234:237], s[2:3] offset:32
	v_mov_b32_e32 v238, v171
	v_mov_b32_e32 v239, v175
	v_mov_b32_e32 v240, v179
	v_mov_b32_e32 v241, v183
	global_store_dwordx4 v145, v[238:241], s[2:3] offset:48
	s_waitcnt vmcnt(24)
	v_mov_b32_e32 v128, v200
	v_mov_b32_e32 v129, v204
	v_mov_b32_e32 v130, v212
	v_mov_b32_e32 v131, v230
	v_mov_b32_e32 v132, v201
	v_mov_b32_e32 v133, v205
	v_mov_b32_e32 v134, v213
	v_mov_b32_e32 v135, v231
	v_mov_b32_e32 v136, v202
	v_mov_b32_e32 v137, v206
	v_mov_b32_e32 v138, v214
	v_mov_b32_e32 v139, v232
	v_mov_b32_e32 v140, v203
	v_mov_b32_e32 v141, v207
	v_mov_b32_e32 v142, v215
	v_mov_b32_e32 v143, v233
	v_mfma_f32_16x16x4_f32 v[128:131], v64, v168, v[128:131]
	v_mfma_f32_16x16x4_f32 v[132:135], v65, v168, v[132:135]
	v_mfma_f32_16x16x4_f32 v[136:139], v66, v168, v[136:139]
	v_mfma_f32_16x16x4_f32 v[140:143], v67, v168, v[140:143]
	v_mfma_f32_16x16x4_f32 v[128:131], v80, v169, v[128:131]
	v_mfma_f32_16x16x4_f32 v[132:135], v81, v169, v[132:135]
	v_mfma_f32_16x16x4_f32 v[136:139], v82, v169, v[136:139]
	v_mfma_f32_16x16x4_f32 v[140:143], v83, v169, v[140:143]
	v_mfma_f32_16x16x4_f32 v[128:131], v96, v170, v[128:131]
	v_mfma_f32_16x16x4_f32 v[132:135], v97, v170, v[132:135]
	v_mfma_f32_16x16x4_f32 v[136:139], v98, v170, v[136:139]
	v_mfma_f32_16x16x4_f32 v[140:143], v99, v170, v[140:143]
	v_mfma_f32_16x16x4_f32 v[128:131], v112, v171, v[128:131]
	v_mfma_f32_16x16x4_f32 v[132:135], v113, v171, v[132:135]
	v_mfma_f32_16x16x4_f32 v[136:139], v114, v171, v[136:139]
	v_mfma_f32_16x16x4_f32 v[140:143], v115, v171, v[140:143]
	v_mfma_f32_16x16x4_f32 v[128:131], v68, v172, v[128:131]
	v_mfma_f32_16x16x4_f32 v[132:135], v69, v172, v[132:135]
	v_mfma_f32_16x16x4_f32 v[136:139], v70, v172, v[136:139]
	v_mfma_f32_16x16x4_f32 v[140:143], v71, v172, v[140:143]
	v_mfma_f32_16x16x4_f32 v[128:131], v84, v173, v[128:131]
	v_mfma_f32_16x16x4_f32 v[132:135], v85, v173, v[132:135]
	v_mfma_f32_16x16x4_f32 v[136:139], v86, v173, v[136:139]
	v_mfma_f32_16x16x4_f32 v[140:143], v87, v173, v[140:143]
	v_mfma_f32_16x16x4_f32 v[128:131], v100, v174, v[128:131]
	v_mfma_f32_16x16x4_f32 v[132:135], v101, v174, v[132:135]
	v_mfma_f32_16x16x4_f32 v[136:139], v102, v174, v[136:139]
	v_mfma_f32_16x16x4_f32 v[140:143], v103, v174, v[140:143]
	v_mfma_f32_16x16x4_f32 v[128:131], v116, v175, v[128:131]
	v_mfma_f32_16x16x4_f32 v[132:135], v117, v175, v[132:135]
	v_mfma_f32_16x16x4_f32 v[136:139], v118, v175, v[136:139]
	v_mfma_f32_16x16x4_f32 v[140:143], v119, v175, v[140:143]
	v_mfma_f32_16x16x4_f32 v[128:131], v72, v176, v[128:131]
	v_mfma_f32_16x16x4_f32 v[132:135], v73, v176, v[132:135]
	v_mfma_f32_16x16x4_f32 v[136:139], v74, v176, v[136:139]
	v_mfma_f32_16x16x4_f32 v[140:143], v75, v176, v[140:143]
	v_mfma_f32_16x16x4_f32 v[128:131], v88, v177, v[128:131]
	v_mfma_f32_16x16x4_f32 v[132:135], v89, v177, v[132:135]
	v_mfma_f32_16x16x4_f32 v[136:139], v90, v177, v[136:139]
	v_mfma_f32_16x16x4_f32 v[140:143], v91, v177, v[140:143]
	v_mfma_f32_16x16x4_f32 v[128:131], v104, v178, v[128:131]
	v_mfma_f32_16x16x4_f32 v[132:135], v105, v178, v[132:135]
	v_mfma_f32_16x16x4_f32 v[136:139], v106, v178, v[136:139]
	v_mfma_f32_16x16x4_f32 v[140:143], v107, v178, v[140:143]
	v_mfma_f32_16x16x4_f32 v[128:131], v120, v179, v[128:131]
	v_mfma_f32_16x16x4_f32 v[132:135], v121, v179, v[132:135]
	v_mfma_f32_16x16x4_f32 v[136:139], v122, v179, v[136:139]
	v_mfma_f32_16x16x4_f32 v[140:143], v123, v179, v[140:143]
	v_mfma_f32_16x16x4_f32 v[128:131], v76, v180, v[128:131]
	v_mfma_f32_16x16x4_f32 v[132:135], v77, v180, v[132:135]
	v_mfma_f32_16x16x4_f32 v[136:139], v78, v180, v[136:139]
	v_mfma_f32_16x16x4_f32 v[140:143], v79, v180, v[140:143]
	v_mfma_f32_16x16x4_f32 v[128:131], v92, v181, v[128:131]
	v_mfma_f32_16x16x4_f32 v[132:135], v93, v181, v[132:135]
	v_mfma_f32_16x16x4_f32 v[136:139], v94, v181, v[136:139]
	v_mfma_f32_16x16x4_f32 v[140:143], v95, v181, v[140:143]
	v_mfma_f32_16x16x4_f32 v[128:131], v108, v182, v[128:131]
	v_mfma_f32_16x16x4_f32 v[132:135], v109, v182, v[132:135]
	v_mfma_f32_16x16x4_f32 v[136:139], v110, v182, v[136:139]
	v_mfma_f32_16x16x4_f32 v[140:143], v111, v182, v[140:143]
	v_mfma_f32_16x16x4_f32 v[128:131], v124, v183, v[128:131]
	v_mfma_f32_16x16x4_f32 v[132:135], v125, v183, v[132:135]
	v_mfma_f32_16x16x4_f32 v[136:139], v126, v183, v[136:139]
	v_mfma_f32_16x16x4_f32 v[140:143], v127, v183, v[140:143]
	s_mov_b64 s[0:1], s[4:5]
	s_mov_b64 s[2:3], s[6:7]
	s_add_i32 s9, s9, 1
	s_cmp_eq_u32 s9, 8
	s_cbranch_scc0 .Lp2_l1_loop
	s_nop 7
	s_nop 3

; __device__ __forceinline__ void stage_rwkv_pass2(const Params& P, int level) {
;     ...
;     if (level == 0) {
;         const bool spread = (gridDim.x == 256);
;         for (int it0 = spread ? (wave < 4 ? (int)blockIdx.x : P2_NG * 64) : gw; it0 < P2_NG * 8 * 8; it0 += spread ? P2_NG * 64 : ngw) {
;             int it = it0;
;             if (spread) { const int x = blockIdx.x & 7, j = blockIdx.x >> 3, idx = wave * 32 + j; it = ((idx >> 3) * 8 + x) * 8 + (idx & 7); }
.LBB0_241:
	s_andn2_b64 vcc, exec, s[0:1]
	s_cbranch_vccnz .LBB0_253
	v_readfirstlane_b32 s0, v211
	s_lshr_b32 s11, s0, 6
	s_cmpk_eq_i32 s62, 0x100
	s_cselect_b32 s12, 1, 0
	s_cbranch_scc0 .Lp2l0_gen
	s_cmp_lt_u32 s11, 4
	s_cselect_b32 s8, s54, 0x400
	s_movk_i32 s16, 0x400
	s_branch .Lp2l0_go

; template <bool HAS_C, bool STORE_STEPS>
; __device__ __forceinline__ void chain16(f32x4 (&acc)[4], const float* Mb, size_t mstride, float* Cb, size_t cstride, int nsteps) {
;     f32x4 mc[16];
; #pragma unroll
;     for (int i = 0; i < 16; ++i) mc[i] = *(const f32x4*)(Mb + (size_t)i * 64);
; __device__ __forceinline__ void stage_rwkv_pass2(const Params& P, int level) {
;     ...
;         for (int it0 = spread ? (wave < 4 ? (int)blockIdx.x : P2_NG * 64) : gw; it0 < P2_NG * 8 * 8; it0 += spread ? P2_NG * 64 : ngw) {
;             int it = it0;
;             if (spread) { const int x = blockIdx.x & 7, j = blockIdx.x >> 3, idx = wave * 32 + j; it = ((idx >> 3) * 8 + x) * 8 + (idx & 7); }
;             const int g = it >> 6, h = (it >> 3) & 7, part = (it >> 2) & 1, s = it & 3, v = 16 * s + rho;
;             const float* Mb = MCM + ((size_t)(g * P2_GS) * 8 + h) * 4096 + (size_t)(16 * g4) * 64 + 4 * rho;
;             float* Cb = MCC + ((size_t)(g * P2_GS) * 8 + h) * 4096 + (size_t)v * 64 + 16 * g4;
;             if (part == 0) {
; #pragma unroll
;                 for (int n = 0; n < 4; ++n)
; #pragma unroll
;                     for (int j = 0; j < 4; ++j) acc[n][j] = (v == 16 * g4 + 4 * j + n) ? 1.f : 0.f;
;                 chain16<false, false>(acc, Mb, 32768, Cb, 32768, P2_GS);
.Lp2l0_go:
	s_cmpk_gt_i32 s8, 0x3ff
	s_cbranch_scc1 .Lp2l0_end
	v_and_b32_e32 v146, 63, v211
	v_and_b32_e32 v147, 15, v146
	v_lshrrev_b32_e32 v148, 4, v146
	v_lshlrev_b32_e32 v144, 12, v148
	v_lshl_add_u32 v144, v147, 4, v144
	v_lshlrev_b32_e32 v145, 6, v148
	v_lshl_add_u32 v145, v147, 8, v145
.Lp2l0_item:
	s_mov_b32 s13, s8
	s_cmp_eq_u32 s12, 0
	s_cbranch_scc1 .Lp2l0_map
	s_and_b32 s14, s54, 7
	s_lshr_b32 s15, s54, 3
	s_lshl_b32 s13, s11, 5
	s_add_i32 s15, s13, s15
	s_lshr_b32 s13, s15, 3
	s_lshl_b32 s13, s13, 3
	s_add_i32 s13, s13, s14
	s_lshl_b32 s13, s13, 3
	s_and_b32 s15, s15, 7
	s_add_i32 s13, s13, s15
.Lp2l0_map:
	s_lshr_b32 s14, s13, 6
	s_bfe_u32 s15, s13, 0x30003
	s_and_b32 s17, s13, 3
	s_lshl_b32 s18, s14, 7
	s_add_i32 s18, s18, s15
	s_lshl_b32 s18, s18, 14
	s_lshl_b32 s19, s17, 12
	s_add_u32 s0, s72, 0x10880000
	s_addc_u32 s1, s73, 0
	s_add_u32 s0, s0, s18
	s_addc_u32 s1, s1, 0
	s_add_u32 s2, s72, 0x12880000
	s_addc_u32 s3, s73, 0
	s_add_u32 s2, s2, s18
	s_addc_u32 s3, s3, 0
	s_add_u32 s2, s2, s19
	s_addc_u32 s3, s3, 0
	s_lshl_b32 s18, s14, 3
	s_add_i32 s18, s18, s15
	s_lshl_b32 s18, s18, 14
	s_add_i32 s18, s18, s19
	s_bitcmp1_b32 s13, 2
	s_cbranch_scc1 .Lp2l0_c
	v_mov_b32_e32 v149, 0xff
	v_cmp_eq_u32_e32 vcc, s17, v148
	s_nop 1
	v_cndmask_b32_e32 v149, v149, v147, vcc
	v_cmp_eq_u32_e32 vcc, 0, v149
	s_nop 1
	v_cndmask_b32_e64 v128, 0, 1.0, vcc
	v_cmp_eq_u32_e32 vcc, 4, v149
	s_nop 1
	v_cndmask_b32_e64 v129, 0, 1.0, vcc
	v_cmp_eq_u32_e32 vcc, 8, v149
	s_nop 1
	v_cndmask_b32_e64 v130, 0, 1.0, vcc
	v_cmp_eq_u32_e32 vcc, 12, v149
	s_nop 1
	v_cndmask_b32_e64 v131, 0, 1.0, vcc
	v_cmp_eq_u32_e32 vcc, 1, v149
	s_nop 1
	v_cndmask_b32_e64 v132, 0, 1.0, vcc
	v_cmp_eq_u32_e32 vcc, 5, v149
	s_nop 1
	v_cndmask_b32_e64 v133, 0, 1.0, vcc
	v_cmp_eq_u32_e32 vcc, 9, v149
	s_nop 1
	v_cndmask_b32_e64 v134, 0, 1.0, vcc
	v_cmp_eq_u32_e32 vcc, 13, v149
	s_nop 1
	v_cndmask_b32_e64 v135, 0, 1.0, vcc
	v_cmp_eq_u32_e32 vcc, 2, v149
	s_nop 1
	v_cndmask_b32_e64 v136, 0, 1.0, vcc
	v_cmp_eq_u32_e32 vcc, 6, v149
	s_nop 1
	v_cndmask_b32_e64 v137, 0, 1.0, vcc
	v_cmp_eq_u32_e32 vcc, 10, v149
	s_nop 1
	v_cndmask_b32_e64 v138, 0, 1.0, vcc
	v_cmp_eq_u32_e32 vcc, 14, v149
	s_nop 1
	v_cndmask_b32_e64 v139, 0, 1.0, vcc
	v_cmp_eq_u32_e32 vcc, 3, v149
	s_nop 1
	v_cndmask_b32_e64 v140, 0, 1.0, vcc
	v_cmp_eq_u32_e32 vcc, 7, v149
	s_nop 1
	v_cndmask_b32_e64 v141, 0, 1.0, vcc
	v_cmp_eq_u32_e32 vcc, 11, v149
	s_nop 1
	v_cndmask_b32_e64 v142, 0, 1.0, vcc
	v_cmp_eq_u32_e32 vcc, 15, v149
	s_nop 1
	v_cndmask_b32_e64 v143, 0, 1.0, vcc
	global_load_dwordx4 v[0:3], v144, s[0:1]
	global_load_dwordx4 v[4:7], v144, s[0:1] offset:256
	global_load_dwordx4 v[8:11], v144, s[0:1] offset:512
	global_load_dwordx4 v[12:15], v144, s[0:1] offset:768
	global_load_dwordx4 v[16:19], v144, s[0:1] offset:1024
	global_load_dwordx4 v[20:23], v144, s[0:1] offset:1280
	global_load_dwordx4 v[24:27], v144, s[0:1] offset:1536
	global_load_dwordx4 v[28:31], v144, s[0:1] offset:1792
	global_load_dwordx4 v[32:35], v144, s[0:1] offset:2048
	global_load_dwordx4 v[36:39], v144, s[0:1] offset:2304
	global_load_dwordx4 v[40:43], v144, s[0:1] offset:2560
	global_load_dwordx4 v[44:47], v144, s[0:1] offset:2816
	global_load_dwordx4 v[48:51], v144, s[0:1] offset:3072
	global_load_dwordx4 v[52:55], v144, s[0:1] offset:3328
	global_load_dwordx4 v[56:59], v144, s[0:1] offset:3584
	global_load_dwordx4 v[60:63], v144, s[0:1] offset:3840
	s_mov_b32 s9, 0
.Lp2_l0m_loop:
	s_mov_b32 s10, 0x20000
	s_add_u32 s4, s0, s10
	s_addc_u32 s5, s1, 0
	s_add_u32 s6, s2, s10
	s_addc_u32 s7, s3, 0
	global_load_dwordx4 v[64:67], v144, s[4:5]
	global_load_dwordx4 v[68:71], v144, s[4:5] offset:256
	global_load_dwordx4 v[72:75], v144, s[4:5] offset:512
	global_load_dwordx4 v[76:79], v144, s[4:5] offset:768
	global_load_dwordx4 v[80:83], v144, s[4:5] offset:1024
	global_load_dwordx4 v[84:87], v144, s[4:5] offset:1280
	global_load_dwordx4 v[88:91], v144, s[4:5] offset:1536
	global_load_dwordx4 v[92:95], v144, s[4:5] offset:1792
	global_load_dwordx4 v[96:99], v144, s[4:5] offset:2048
	global_load_dwordx4 v[100:103], v144, s[4:5] offset:2304
	global_load_dwordx4 v[104:107], v144, s[4:5] offset:2560
	global_load_dwordx4 v[108:111], v144, s[4:5] offset:2816
	global_load_dwordx4 v[112:115], v144, s[4:5] offset:3072
	global_load_dwordx4 v[116:119], v144, s[4:5] offset:3328
	global_load_dwordx4 v[120:123], v144, s[4:5] offset:3584
	global_load_dwordx4 v[124:127], v144, s[4:5] offset:3840
	s_waitcnt vmcnt(16)
; template <bool HAS_C, bool STORE_STEPS>
; __device__ __forceinline__ void chain16(f32x4 (&acc)[4], const float* Mb, size_t mstride, float* Cb, size_t cstride, int nsteps) {
;     ...
;     for (int c = 0; c < nsteps; ++c) {
;         float* cp = Cb + (size_t)c * cstride;
;         f32x4 q[4];
;         if (HAS_C) {
; #pragma unroll
;             for (int j = 0; j < 4; ++j) q[j] = qn[j];
;             const float* cn = Cb + (size_t)(c + 1 < nsteps ? c + 1 : c) * cstride;
; #pragma unroll
;             for (int j = 0; j < 4; ++j) qn[j] = *(const f32x4*)(cn + 4 * j);
;         }
;         f32x4 mn[16];
;         const float* Mn = Mb + (size_t)(c + 1 < nsteps ? c + 1 : c) * mstride;
; #pragma unroll
;         for (int i = 0; i < 16; ++i) mn[i] = *(const f32x4*)(Mn + (size_t)i * 64);
;         if (STORE_STEPS) {
; #pragma unroll
;             for (int j = 0; j < 4; ++j) *(f32x4*)(cp + 4 * j) = (f32x4){acc[0][j], acc[1][j], acc[2][j], acc[3][j]};
;         }
;         f32x4 na[4];
; #pragma unroll
;         for (int n = 0; n < 4; ++n) na[n] = HAS_C ? (f32x4){q[0][n], q[1][n], q[2][n], q[3][n]} : (f32x4){0.f, 0.f, 0.f, 0.f};
; #pragma unroll
;         for (int n = 0; n < 4; ++n)
; #pragma unroll
;             for (int j = 0; j < 4; ++j) {
;                 const f32x4 a4 = mc[4 * j + n];
; #pragma unroll
;                 for (int np = 0; np < 4; ++np) na[np] = __builtin_amdgcn_mfma_f32_16x16x4f32(a4[np], acc[n][j], na[np], 0, 0, 0);
;             }
; #pragma unroll
;         for (int n = 0; n < 4; ++n) acc[n] = na[n];
; #pragma unroll
;         for (int i = 0; i < 16; ++i) mc[i] = mn[i];
;     }
	v_mov_b32_e32 v168, 0
	v_mov_b32_e32 v169, 0
	v_mov_b32_e32 v170, 0
	v_mov_b32_e32 v171, 0
	v_mov_b32_e32 v172, 0
	v_mov_b32_e32 v173, 0
	v_mov_b32_e32 v174, 0
	v_mov_b32_e32 v175, 0
	v_mov_b32_e32 v176, 0
	v_mov_b32_e32 v177, 0
	v_mov_b32_e32 v178, 0
	v_mov_b32_e32 v179, 0
	v_mov_b32_e32 v180, 0
	v_mov_b32_e32 v181, 0
	v_mov_b32_e32 v182, 0
	v_mov_b32_e32 v183, 0
	v_mfma_f32_16x16x4_f32 v[168:171], v0, v128, v[168:171]
	v_mfma_f32_16x16x4_f32 v[172:175], v1, v128, v[172:175]
	v_mfma_f32_16x16x4_f32 v[176:179], v2, v128, v[176:179]
	v_mfma_f32_16x16x4_f32 v[180:183], v3, v128, v[180:183]
	v_mfma_f32_16x16x4_f32 v[168:171], v16, v129, v[168:171]
	v_mfma_f32_16x16x4_f32 v[172:175], v17, v129, v[172:175]
	v_mfma_f32_16x16x4_f32 v[176:179], v18, v129, v[176:179]
	v_mfma_f32_16x16x4_f32 v[180:183], v19, v129, v[180:183]
	v_mfma_f32_16x16x4_f32 v[168:171], v32, v130, v[168:171]
	v_mfma_f32_16x16x4_f32 v[172:175], v33, v130, v[172:175]
	v_mfma_f32_16x16x4_f32 v[176:179], v34, v130, v[176:179]
	v_mfma_f32_16x16x4_f32 v[180:183], v35, v130, v[180:183]
	v_mfma_f32_16x16x4_f32 v[168:171], v48, v131, v[168:171]
	v_mfma_f32_16x16x4_f32 v[172:175], v49, v131, v[172:175]
	v_mfma_f32_16x16x4_f32 v[176:179], v50, v131, v[176:179]
	v_mfma_f32_16x16x4_f32 v[180:183], v51, v131, v[180:183]
	v_mfma_f32_16x16x4_f32 v[168:171], v4, v132, v[168:171]
	v_mfma_f32_16x16x4_f32 v[172:175], v5, v132, v[172:175]
	v_mfma_f32_16x16x4_f32 v[176:179], v6, v132, v[176:179]
	v_mfma_f32_16x16x4_f32 v[180:183], v7, v132, v[180:183]
	v_mfma_f32_16x16x4_f32 v[168:171], v20, v133, v[168:171]
	v_mfma_f32_16x16x4_f32 v[172:175], v21, v133, v[172:175]
	v_mfma_f32_16x16x4_f32 v[176:179], v22, v133, v[176:179]
	v_mfma_f32_16x16x4_f32 v[180:183], v23, v133, v[180:183]
	v_mfma_f32_16x16x4_f32 v[168:171], v36, v134, v[168:171]
	v_mfma_f32_16x16x4_f32 v[172:175], v37, v134, v[172:175]
	v_mfma_f32_16x16x4_f32 v[176:179], v38, v134, v[176:179]
	v_mfma_f32_16x16x4_f32 v[180:183], v39, v134, v[180:183]
	v_mfma_f32_16x16x4_f32 v[168:171], v52, v135, v[168:171]
	v_mfma_f32_16x16x4_f32 v[172:175], v53, v135, v[172:175]
	v_mfma_f32_16x16x4_f32 v[176:179], v54, v135, v[176:179]
	v_mfma_f32_16x16x4_f32 v[180:183], v55, v135, v[180:183]
	v_mfma_f32_16x16x4_f32 v[168:171], v8, v136, v[168:171]
	v_mfma_f32_16x16x4_f32 v[172:175], v9, v136, v[172:175]
	v_mfma_f32_16x16x4_f32 v[176:179], v10, v136, v[176:179]
	v_mfma_f32_16x16x4_f32 v[180:183], v11, v136, v[180:183]
	v_mfma_f32_16x16x4_f32 v[168:171], v24, v137, v[168:171]
	v_mfma_f32_16x16x4_f32 v[172:175], v25, v137, v[172:175]
	v_mfma_f32_16x16x4_f32 v[176:179], v26, v137, v[176:179]
	v_mfma_f32_16x16x4_f32 v[180:183], v27, v137, v[180:183]
	v_mfma_f32_16x16x4_f32 v[168:171], v40, v138, v[168:171]
	v_mfma_f32_16x16x4_f32 v[172:175], v41, v138, v[172:175]
	v_mfma_f32_16x16x4_f32 v[176:179], v42, v138, v[176:179]
	v_mfma_f32_16x16x4_f32 v[180:183], v43, v138, v[180:183]
	v_mfma_f32_16x16x4_f32 v[168:171], v56, v139, v[168:171]
	v_mfma_f32_16x16x4_f32 v[172:175], v57, v139, v[172:175]
	v_mfma_f32_16x16x4_f32 v[176:179], v58, v139, v[176:179]
	v_mfma_f32_16x16x4_f32 v[180:183], v59, v139, v[180:183]
	v_mfma_f32_16x16x4_f32 v[168:171], v12, v140, v[168:171]
	v_mfma_f32_16x16x4_f32 v[172:175], v13, v140, v[172:175]
	v_mfma_f32_16x16x4_f32 v[176:179], v14, v140, v[176:179]
	v_mfma_f32_16x16x4_f32 v[180:183], v15, v140, v[180:183]
	v_mfma_f32_16x16x4_f32 v[168:171], v28, v141, v[168:171]
	v_mfma_f32_16x16x4_f32 v[172:175], v29, v141, v[172:175]
	v_mfma_f32_16x16x4_f32 v[176:179], v30, v141, v[176:179]
	v_mfma_f32_16x16x4_f32 v[180:183], v31, v141, v[180:183]
	v_mfma_f32_16x16x4_f32 v[168:171], v44, v142, v[168:171]
	v_mfma_f32_16x16x4_f32 v[172:175], v45, v142, v[172:175]
	v_mfma_f32_16x16x4_f32 v[176:179], v46, v142, v[176:179]
	v_mfma_f32_16x16x4_f32 v[180:183], v47, v142, v[180:183]
	v_mfma_f32_16x16x4_f32 v[168:171], v60, v143, v[168:171]
	v_mfma_f32_16x16x4_f32 v[172:175], v61, v143, v[172:175]
	v_mfma_f32_16x16x4_f32 v[176:179], v62, v143, v[176:179]
	v_mfma_f32_16x16x4_f32 v[180:183], v63, v143, v[180:183]
	s_mov_b64 s[0:1], s[4:5]
	s_mov_b64 s[2:3], s[6:7]
	s_cmp_eq_u32 s9, 7
	s_cselect_b32 s10, 0, 0x20000
	s_add_u32 s4, s0, s10
	s_addc_u32 s5, s1, 0
	s_add_u32 s6, s2, s10
	s_addc_u32 s7, s3, 0
	global_load_dwordx4 v[0:3], v144, s[4:5]
	global_load_dwordx4 v[4:7], v144, s[4:5] offset:256
	global_load_dwordx4 v[8:11], v144, s[4:5] offset:512
	global_load_dwordx4 v[12:15], v144, s[4:5] offset:768
	global_load_dwordx4 v[16:19], v144, s[4:5] offset:1024
	global_load_dwordx4 v[20:23], v144, s[4:5] offset:1280
	global_load_dwordx4 v[24:27], v144, s[4:5] offset:1536
	global_load_dwordx4 v[28:31], v144, s[4:5] offset:1792
	global_load_dwordx4 v[32:35], v144, s[4:5] offset:2048
	global_load_dwordx4 v[36:39], v144, s[4:5] offset:2304
	global_load_dwordx4 v[40:43], v144, s[4:5] offset:2560
	global_load_dwordx4 v[44:47], v144, s[4:5] offset:2816
	global_load_dwordx4 v[48:51], v144, s[4:5] offset:3072
	global_load_dwordx4 v[52:55], v144, s[4:5] offset:3328
	global_load_dwordx4 v[56:59], v144, s[4:5] offset:3584
	global_load_dwordx4 v[60:63], v144, s[4:5] offset:3840
	s_waitcnt vmcnt(16)
; template <bool HAS_C, bool STORE_STEPS>
; __device__ __forceinline__ void chain16(f32x4 (&acc)[4], const float* Mb, size_t mstride, float* Cb, size_t cstride, int nsteps) {
;     ...
;     for (int c = 0; c < nsteps; ++c) {
;         float* cp = Cb + (size_t)c * cstride;
;         f32x4 q[4];
;         if (HAS_C) {
; #pragma unroll
;             for (int j = 0; j < 4; ++j) q[j] = qn[j];
;             const float* cn = Cb + (size_t)(c + 1 < nsteps ? c + 1 : c) * cstride;
; #pragma unroll
;             for (int j = 0; j < 4; ++j) qn[j] = *(const f32x4*)(cn + 4 * j);
;         }
;         f32x4 mn[16];
;         const float* Mn = Mb + (size_t)(c + 1 < nsteps ? c + 1 : c) * mstride;
; #pragma unroll
;         for (int i = 0; i < 16; ++i) mn[i] = *(const f32x4*)(Mn + (size_t)i * 64);
;         if (STORE_STEPS) {
; #pragma unroll
;             for (int j = 0; j < 4; ++j) *(f32x4*)(cp + 4 * j) = (f32x4){acc[0][j], acc[1][j], acc[2][j], acc[3][j]};
;         }
;         f32x4 na[4];
; #pragma unroll
;         for (int n = 0; n < 4; ++n) na[n] = HAS_C ? (f32x4){q[0][n], q[1][n], q[2][n], q[3][n]} : (f32x4){0.f, 0.f, 0.f, 0.f};
; #pragma unroll
;         for (int n = 0; n < 4; ++n)
; #pragma unroll
;             for (int j = 0; j < 4; ++j) {
;                 const f32x4 a4 = mc[4 * j + n];
; #pragma unroll
;                 for (int np = 0; np < 4; ++np) na[np] = __builtin_amdgcn_mfma_f32_16x16x4f32(a4[np], acc[n][j], na[np], 0, 0, 0);
;             }
; #pragma unroll
;         for (int n = 0; n < 4; ++n) acc[n] = na[n];
; #pragma unroll
;         for (int i = 0; i < 16; ++i) mc[i] = mn[i];
;     }
; __device__ __forceinline__ void stage_rwkv_pass2(const Params& P, int level) {
;     ...
;             } else {
; #pragma unroll
;                 for (int n = 0; n < 4; ++n) acc[n] = (f32x4){0.f, 0.f, 0.f, 0.f};
;                 chain16<true, false>(acc, Mb, 32768, Cb, 32768, P2_GS);
;                 store_strip(acc, CG + ((size_t)g * 8 + h) * 4096 + (size_t)v * 64 + 16 * g4);
	v_mov_b32_e32 v128, 0
	v_mov_b32_e32 v129, 0
	v_mov_b32_e32 v130, 0
	v_mov_b32_e32 v131, 0
	v_mov_b32_e32 v132, 0
	v_mov_b32_e32 v133, 0
	v_mov_b32_e32 v134, 0
	v_mov_b32_e32 v135, 0
	v_mov_b32_e32 v136, 0
	v_mov_b32_e32 v137, 0
	v_mov_b32_e32 v138, 0
	v_mov_b32_e32 v139, 0
	v_mov_b32_e32 v140, 0
	v_mov_b32_e32 v141, 0
	v_mov_b32_e32 v142, 0
	v_mov_b32_e32 v143, 0
	v_mfma_f32_16x16x4_f32 v[128:131], v64, v168, v[128:131]
	v_mfma_f32_16x16x4_f32 v[132:135], v65, v168, v[132:135]
	v_mfma_f32_16x16x4_f32 v[136:139], v66, v168, v[136:139]
	v_mfma_f32_16x16x4_f32 v[140:143], v67, v168, v[140:143]
	v_mfma_f32_16x16x4_f32 v[128:131], v80, v169, v[128:131]
	v_mfma_f32_16x16x4_f32 v[132:135], v81, v169, v[132:135]
	v_mfma_f32_16x16x4_f32 v[136:139], v82, v169, v[136:139]
	v_mfma_f32_16x16x4_f32 v[140:143], v83, v169, v[140:143]
	v_mfma_f32_16x16x4_f32 v[128:131], v96, v170, v[128:131]
	v_mfma_f32_16x16x4_f32 v[132:135], v97, v170, v[132:135]
	v_mfma_f32_16x16x4_f32 v[136:139], v98, v170, v[136:139]
	v_mfma_f32_16x16x4_f32 v[140:143], v99, v170, v[140:143]
	v_mfma_f32_16x16x4_f32 v[128:131], v112, v171, v[128:131]
	v_mfma_f32_16x16x4_f32 v[132:135], v113, v171, v[132:135]
	v_mfma_f32_16x16x4_f32 v[136:139], v114, v171, v[136:139]
	v_mfma_f32_16x16x4_f32 v[140:143], v115, v171, v[140:143]
	v_mfma_f32_16x16x4_f32 v[128:131], v68, v172, v[128:131]
	v_mfma_f32_16x16x4_f32 v[132:135], v69, v172, v[132:135]
	v_mfma_f32_16x16x4_f32 v[136:139], v70, v172, v[136:139]
	v_mfma_f32_16x16x4_f32 v[140:143], v71, v172, v[140:143]
	v_mfma_f32_16x16x4_f32 v[128:131], v84, v173, v[128:131]
	v_mfma_f32_16x16x4_f32 v[132:135], v85, v173, v[132:135]
	v_mfma_f32_16x16x4_f32 v[136:139], v86, v173, v[136:139]
	v_mfma_f32_16x16x4_f32 v[140:143], v87, v173, v[140:143]
	v_mfma_f32_16x16x4_f32 v[128:131], v100, v174, v[128:131]
	v_mfma_f32_16x16x4_f32 v[132:135], v101, v174, v[132:135]
	v_mfma_f32_16x16x4_f32 v[136:139], v102, v174, v[136:139]
	v_mfma_f32_16x16x4_f32 v[140:143], v103, v174, v[140:143]
	v_mfma_f32_16x16x4_f32 v[128:131], v116, v175, v[128:131]
	v_mfma_f32_16x16x4_f32 v[132:135], v117, v175, v[132:135]
	v_mfma_f32_16x16x4_f32 v[136:139], v118, v175, v[136:139]
	v_mfma_f32_16x16x4_f32 v[140:143], v119, v175, v[140:143]
	v_mfma_f32_16x16x4_f32 v[128:131], v72, v176, v[128:131]
	v_mfma_f32_16x16x4_f32 v[132:135], v73, v176, v[132:135]
	v_mfma_f32_16x16x4_f32 v[136:139], v74, v176, v[136:139]
	v_mfma_f32_16x16x4_f32 v[140:143], v75, v176, v[140:143]
	v_mfma_f32_16x16x4_f32 v[128:131], v88, v177, v[128:131]
	v_mfma_f32_16x16x4_f32 v[132:135], v89, v177, v[132:135]
	v_mfma_f32_16x16x4_f32 v[136:139], v90, v177, v[136:139]
	v_mfma_f32_16x16x4_f32 v[140:143], v91, v177, v[140:143]
	v_mfma_f32_16x16x4_f32 v[128:131], v104, v178, v[128:131]
	v_mfma_f32_16x16x4_f32 v[132:135], v105, v178, v[132:135]
	v_mfma_f32_16x16x4_f32 v[136:139], v106, v178, v[136:139]
	v_mfma_f32_16x16x4_f32 v[140:143], v107, v178, v[140:143]
	v_mfma_f32_16x16x4_f32 v[128:131], v120, v179, v[128:131]
	v_mfma_f32_16x16x4_f32 v[132:135], v121, v179, v[132:135]
	v_mfma_f32_16x16x4_f32 v[136:139], v122, v179, v[136:139]
	v_mfma_f32_16x16x4_f32 v[140:143], v123, v179, v[140:143]
	v_mfma_f32_16x16x4_f32 v[128:131], v76, v180, v[128:131]
	v_mfma_f32_16x16x4_f32 v[132:135], v77, v180, v[132:135]
	v_mfma_f32_16x16x4_f32 v[136:139], v78, v180, v[136:139]
	v_mfma_f32_16x16x4_f32 v[140:143], v79, v180, v[140:143]
	v_mfma_f32_16x16x4_f32 v[128:131], v92, v181, v[128:131]
	v_mfma_f32_16x16x4_f32 v[132:135], v93, v181, v[132:135]
	v_mfma_f32_16x16x4_f32 v[136:139], v94, v181, v[136:139]
	v_mfma_f32_16x16x4_f32 v[140:143], v95, v181, v[140:143]
	v_mfma_f32_16x16x4_f32 v[128:131], v108, v182, v[128:131]
	v_mfma_f32_16x16x4_f32 v[132:135], v109, v182, v[132:135]
	v_mfma_f32_16x16x4_f32 v[136:139], v110, v182, v[136:139]
	v_mfma_f32_16x16x4_f32 v[140:143], v111, v182, v[140:143]
	v_mfma_f32_16x16x4_f32 v[128:131], v124, v183, v[128:131]
	v_mfma_f32_16x16x4_f32 v[132:135], v125, v183, v[132:135]
	v_mfma_f32_16x16x4_f32 v[136:139], v126, v183, v[136:139]
	v_mfma_f32_16x16x4_f32 v[140:143], v127, v183, v[140:143]
	s_mov_b64 s[0:1], s[4:5]
	s_mov_b64 s[2:3], s[6:7]
	s_add_i32 s9, s9, 1
	s_cmp_eq_u32 s9, 8
	s_cbranch_scc0 .Lp2_l0m_loop
	s_nop 7
	s_nop 3
	s_add_u32 s0, s72, 0x14884000
	s_addc_u32 s1, s73, 0
	s_branch .Lp2l0_st
.Lp2l0_c:
	v_mov_b32_e32 v128, 0
	v_mov_b32_e32 v129, 0
	v_mov_b32_e32 v130, 0
	v_mov_b32_e32 v131, 0
	v_mov_b32_e32 v132, 0
	v_mov_b32_e32 v133, 0
	v_mov_b32_e32 v134, 0
	v_mov_b32_e32 v135, 0
	v_mov_b32_e32 v136, 0
	v_mov_b32_e32 v137, 0
	v_mov_b32_e32 v138, 0
	v_mov_b32_e32 v139, 0
	v_mov_b32_e32 v140, 0
	v_mov_b32_e32 v141, 0
	v_mov_b32_e32 v142, 0
	v_mov_b32_e32 v143, 0
	global_load_dwordx4 v[0:3], v144, s[0:1]
	global_load_dwordx4 v[4:7], v144, s[0:1] offset:256
	global_load_dwordx4 v[8:11], v144, s[0:1] offset:512
	global_load_dwordx4 v[12:15], v144, s[0:1] offset:768
	global_load_dwordx4 v[16:19], v144, s[0:1] offset:1024
	global_load_dwordx4 v[20:23], v144, s[0:1] offset:1280
	global_load_dwordx4 v[24:27], v144, s[0:1] offset:1536
	global_load_dwordx4 v[28:31], v144, s[0:1] offset:1792
	global_load_dwordx4 v[32:35], v144, s[0:1] offset:2048
	global_load_dwordx4 v[36:39], v144, s[0:1] offset:2304
	global_load_dwordx4 v[40:43], v144, s[0:1] offset:2560
	global_load_dwordx4 v[44:47], v144, s[0:1] offset:2816
	global_load_dwordx4 v[48:51], v144, s[0:1] offset:3072
	global_load_dwordx4 v[52:55], v144, s[0:1] offset:3328
	global_load_dwordx4 v[56:59], v144, s[0:1] offset:3584
	global_load_dwordx4 v[60:63], v144, s[0:1] offset:3840
	global_load_dwordx4 v[184:187], v145, s[2:3]
	global_load_dwordx4 v[188:191], v145, s[2:3] offset:16
	global_load_dwordx4 v[192:195], v145, s[2:3] offset:32
	global_load_dwordx4 v[196:199], v145, s[2:3] offset:48
	s_mov_b32 s9, 0
; template <bool HAS_C, bool STORE_STEPS>
; __device__ __forceinline__ void chain16(f32x4 (&acc)[4], const float* Mb, size_t mstride, float* Cb, size_t cstride, int nsteps) {
;     ...
;     for (int c = 0; c < nsteps; ++c) {
;         float* cp = Cb + (size_t)c * cstride;
;         f32x4 q[4];
;         if (HAS_C) {
; #pragma unroll
;             for (int j = 0; j < 4; ++j) q[j] = qn[j];
;             const float* cn = Cb + (size_t)(c + 1 < nsteps ? c + 1 : c) * cstride;
; #pragma unroll
;             for (int j = 0; j < 4; ++j) qn[j] = *(const f32x4*)(cn + 4 * j);
;         }
;         f32x4 mn[16];
;         const float* Mn = Mb + (size_t)(c + 1 < nsteps ? c + 1 : c) * mstride;
; #pragma unroll
;         for (int i = 0; i < 16; ++i) mn[i] = *(const f32x4*)(Mn + (size_t)i * 64);
;         if (STORE_STEPS) {
; #pragma unroll
;             for (int j = 0; j < 4; ++j) *(f32x4*)(cp + 4 * j) = (f32x4){acc[0][j], acc[1][j], acc[2][j], acc[3][j]};
;         }
;         f32x4 na[4];
; #pragma unroll
;         for (int n = 0; n < 4; ++n) na[n] = HAS_C ? (f32x4){q[0][n], q[1][n], q[2][n], q[3][n]} : (f32x4){0.f, 0.f, 0.f, 0.f};
; #pragma unroll
;         for (int n = 0; n < 4; ++n)
; #pragma unroll
;             for (int j = 0; j < 4; ++j) {
;                 const f32x4 a4 = mc[4 * j + n];
; #pragma unroll
;                 for (int np = 0; np < 4; ++np) na[np] = __builtin_amdgcn_mfma_f32_16x16x4f32(a4[np], acc[n][j], na[np], 0, 0, 0);
;             }
; #pragma unroll
;         for (int n = 0; n < 4; ++n) acc[n] = na[n];
; #pragma unroll
;         for (int i = 0; i < 16; ++i) mc[i] = mn[i];
;     }
.Lp2_l0c_loop:
	s_mov_b32 s10, 0x20000
	s_add_u32 s4, s0, s10
	s_addc_u32 s5, s1, 0
	s_add_u32 s6, s2, s10
	s_addc_u32 s7, s3, 0
	global_load_dwordx4 v[64:67], v144, s[4:5]
	global_load_dwordx4 v[68:71], v144, s[4:5] offset:256
	global_load_dwordx4 v[72:75], v144, s[4:5] offset:512
	global_load_dwordx4 v[76:79], v144, s[4:5] offset:768
	global_load_dwordx4 v[80:83], v144, s[4:5] offset:1024
	global_load_dwordx4 v[84:87], v144, s[4:5] offset:1280
	global_load_dwordx4 v[88:91], v144, s[4:5] offset:1536
	global_load_dwordx4 v[92:95], v144, s[4:5] offset:1792
	global_load_dwordx4 v[96:99], v144, s[4:5] offset:2048
	global_load_dwordx4 v[100:103], v144, s[4:5] offset:2304
	global_load_dwordx4 v[104:107], v144, s[4:5] offset:2560
	global_load_dwordx4 v[108:111], v144, s[4:5] offset:2816
	global_load_dwordx4 v[112:115], v144, s[4:5] offset:3072
	global_load_dwordx4 v[116:119], v144, s[4:5] offset:3328
	global_load_dwordx4 v[120:123], v144, s[4:5] offset:3584
	global_load_dwordx4 v[124:127], v144, s[4:5] offset:3840
	global_load_dwordx4 v[200:203], v145, s[6:7]
	global_load_dwordx4 v[204:207], v145, s[6:7] offset:16
	global_load_dwordx4 v[212:215], v145, s[6:7] offset:32
	global_load_dwordx4 v[230:233], v145, s[6:7] offset:48
	s_waitcnt vmcnt(20)
	v_mov_b32_e32 v168, v184
	v_mov_b32_e32 v169, v188
	v_mov_b32_e32 v170, v192
	v_mov_b32_e32 v171, v196
	v_mov_b32_e32 v172, v185
	v_mov_b32_e32 v173, v189
	v_mov_b32_e32 v174, v193
	v_mov_b32_e32 v175, v197
	v_mov_b32_e32 v176, v186
	v_mov_b32_e32 v177, v190
	v_mov_b32_e32 v178, v194
	v_mov_b32_e32 v179, v198
	v_mov_b32_e32 v180, v187
	v_mov_b32_e32 v181, v191
	v_mov_b32_e32 v182, v195
	v_mov_b32_e32 v183, v199
	v_mfma_f32_16x16x4_f32 v[168:171], v0, v128, v[168:171]
	v_mfma_f32_16x16x4_f32 v[172:175], v1, v128, v[172:175]
	v_mfma_f32_16x16x4_f32 v[176:179], v2, v128, v[176:179]
	v_mfma_f32_16x16x4_f32 v[180:183], v3, v128, v[180:183]
	v_mfma_f32_16x16x4_f32 v[168:171], v16, v129, v[168:171]
	v_mfma_f32_16x16x4_f32 v[172:175], v17, v129, v[172:175]
	v_mfma_f32_16x16x4_f32 v[176:179], v18, v129, v[176:179]
	v_mfma_f32_16x16x4_f32 v[180:183], v19, v129, v[180:183]
	v_mfma_f32_16x16x4_f32 v[168:171], v32, v130, v[168:171]
	v_mfma_f32_16x16x4_f32 v[172:175], v33, v130, v[172:175]
	v_mfma_f32_16x16x4_f32 v[176:179], v34, v130, v[176:179]
	v_mfma_f32_16x16x4_f32 v[180:183], v35, v130, v[180:183]
	v_mfma_f32_16x16x4_f32 v[168:171], v48, v131, v[168:171]
	v_mfma_f32_16x16x4_f32 v[172:175], v49, v131, v[172:175]
	v_mfma_f32_16x16x4_f32 v[176:179], v50, v131, v[176:179]
	v_mfma_f32_16x16x4_f32 v[180:183], v51, v131, v[180:183]
	v_mfma_f32_16x16x4_f32 v[168:171], v4, v132, v[168:171]
	v_mfma_f32_16x16x4_f32 v[172:175], v5, v132, v[172:175]
	v_mfma_f32_16x16x4_f32 v[176:179], v6, v132, v[176:179]
	v_mfma_f32_16x16x4_f32 v[180:183], v7, v132, v[180:183]
	v_mfma_f32_16x16x4_f32 v[168:171], v20, v133, v[168:171]
	v_mfma_f32_16x16x4_f32 v[172:175], v21, v133, v[172:175]
	v_mfma_f32_16x16x4_f32 v[176:179], v22, v133, v[176:179]
	v_mfma_f32_16x16x4_f32 v[180:183], v23, v133, v[180:183]
	v_mfma_f32_16x16x4_f32 v[168:171], v36, v134, v[168:171]
	v_mfma_f32_16x16x4_f32 v[172:175], v37, v134, v[172:175]
	v_mfma_f32_16x16x4_f32 v[176:179], v38, v134, v[176:179]
	v_mfma_f32_16x16x4_f32 v[180:183], v39, v134, v[180:183]
	v_mfma_f32_16x16x4_f32 v[168:171], v52, v135, v[168:171]
	v_mfma_f32_16x16x4_f32 v[172:175], v53, v135, v[172:175]
	v_mfma_f32_16x16x4_f32 v[176:179], v54, v135, v[176:179]
	v_mfma_f32_16x16x4_f32 v[180:183], v55, v135, v[180:183]
	v_mfma_f32_16x16x4_f32 v[168:171], v8, v136, v[168:171]
	v_mfma_f32_16x16x4_f32 v[172:175], v9, v136, v[172:175]
	v_mfma_f32_16x16x4_f32 v[176:179], v10, v136, v[176:179]
	v_mfma_f32_16x16x4_f32 v[180:183], v11, v136, v[180:183]
	v_mfma_f32_16x16x4_f32 v[168:171], v24, v137, v[168:171]
	v_mfma_f32_16x16x4_f32 v[172:175], v25, v137, v[172:175]
	v_mfma_f32_16x16x4_f32 v[176:179], v26, v137, v[176:179]
	v_mfma_f32_16x16x4_f32 v[180:183], v27, v137, v[180:183]
	v_mfma_f32_16x16x4_f32 v[168:171], v40, v138, v[168:171]
	v_mfma_f32_16x16x4_f32 v[172:175], v41, v138, v[172:175]
	v_mfma_f32_16x16x4_f32 v[176:179], v42, v138, v[176:179]
	v_mfma_f32_16x16x4_f32 v[180:183], v43, v138, v[180:183]
	v_mfma_f32_16x16x4_f32 v[168:171], v56, v139, v[168:171]
	v_mfma_f32_16x16x4_f32 v[172:175], v57, v139, v[172:175]
	v_mfma_f32_16x16x4_f32 v[176:179], v58, v139, v[176:179]
	v_mfma_f32_16x16x4_f32 v[180:183], v59, v139, v[180:183]
	v_mfma_f32_16x16x4_f32 v[168:171], v12, v140, v[168:171]
	v_mfma_f32_16x16x4_f32 v[172:175], v13, v140, v[172:175]
	v_mfma_f32_16x16x4_f32 v[176:179], v14, v140, v[176:179]
	v_mfma_f32_16x16x4_f32 v[180:183], v15, v140, v[180:183]
	v_mfma_f32_16x16x4_f32 v[168:171], v28, v141, v[168:171]
	v_mfma_f32_16x16x4_f32 v[172:175], v29, v141, v[172:175]
	v_mfma_f32_16x16x4_f32 v[176:179], v30, v141, v[176:179]
	v_mfma_f32_16x16x4_f32 v[180:183], v31, v141, v[180:183]
	v_mfma_f32_16x16x4_f32 v[168:171], v44, v142, v[168:171]
	v_mfma_f32_16x16x4_f32 v[172:175], v45, v142, v[172:175]
	v_mfma_f32_16x16x4_f32 v[176:179], v46, v142, v[176:179]
	v_mfma_f32_16x16x4_f32 v[180:183], v47, v142, v[180:183]
	v_mfma_f32_16x16x4_f32 v[168:171], v60, v143, v[168:171]
	v_mfma_f32_16x16x4_f32 v[172:175], v61, v143, v[172:175]
	v_mfma_f32_16x16x4_f32 v[176:179], v62, v143, v[176:179]
	v_mfma_f32_16x16x4_f32 v[180:183], v63, v143, v[180:183]
	s_mov_b64 s[0:1], s[4:5]
	s_mov_b64 s[2:3], s[6:7]
	s_cmp_eq_u32 s9, 7
	s_cselect_b32 s10, 0, 0x20000
	s_add_u32 s4, s0, s10
	s_addc_u32 s5, s1, 0
	s_add_u32 s6, s2, s10
	s_addc_u32 s7, s3, 0
	global_load_dwordx4 v[0:3], v144, s[4:5]
	global_load_dwordx4 v[4:7], v144, s[4:5] offset:256
	global_load_dwordx4 v[8:11], v144, s[4:5] offset:512
	global_load_dwordx4 v[12:15], v144, s[4:5] offset:768
	global_load_dwordx4 v[16:19], v144, s[4:5] offset:1024
	global_load_dwordx4 v[20:23], v144, s[4:5] offset:1280
	global_load_dwordx4 v[24:27], v144, s[4:5] offset:1536
	global_load_dwordx4 v[28:31], v144, s[4:5] offset:1792
	global_load_dwordx4 v[32:35], v144, s[4:5] offset:2048
	global_load_dwordx4 v[36:39], v144, s[4:5] offset:2304
	global_load_dwordx4 v[40:43], v144, s[4:5] offset:2560
	global_load_dwordx4 v[44:47], v144, s[4:5] offset:2816
	global_load_dwordx4 v[48:51], v144, s[4:5] offset:3072
	global_load_dwordx4 v[52:55], v144, s[4:5] offset:3328
	global_load_dwordx4 v[56:59], v144, s[4:5] offset:3584
	global_load_dwordx4 v[60:63], v144, s[4:5] offset:3840
	global_load_dwordx4 v[184:187], v145, s[6:7]
	global_load_dwordx4 v[188:191], v145, s[6:7] offset:16
	global_load_dwordx4 v[192:195], v145, s[6:7] offset:32
	global_load_dwordx4 v[196:199], v145, s[6:7] offset:48
	s_waitcnt vmcnt(20)
; template <bool HAS_C, bool STORE_STEPS>
; __device__ __forceinline__ void chain16(f32x4 (&acc)[4], const float* Mb, size_t mstride, float* Cb, size_t cstride, int nsteps) {
;     ...
;     for (int c = 0; c < nsteps; ++c) {
;         float* cp = Cb + (size_t)c * cstride;
;         f32x4 q[4];
;         if (HAS_C) {
; #pragma unroll
;             for (int j = 0; j < 4; ++j) q[j] = qn[j];
;             const float* cn = Cb + (size_t)(c + 1 < nsteps ? c + 1 : c) * cstride;
; #pragma unroll
;             for (int j = 0; j < 4; ++j) qn[j] = *(const f32x4*)(cn + 4 * j);
;         }
;         f32x4 mn[16];
;         const float* Mn = Mb + (size_t)(c + 1 < nsteps ? c + 1 : c) * mstride;
; #pragma unroll
;         for (int i = 0; i < 16; ++i) mn[i] = *(const f32x4*)(Mn + (size_t)i * 64);
;         if (STORE_STEPS) {
; #pragma unroll
;             for (int j = 0; j < 4; ++j) *(f32x4*)(cp + 4 * j) = (f32x4){acc[0][j], acc[1][j], acc[2][j], acc[3][j]};
;         }
;         f32x4 na[4];
; #pragma unroll
;         for (int n = 0; n < 4; ++n) na[n] = HAS_C ? (f32x4){q[0][n], q[1][n], q[2][n], q[3][n]} : (f32x4){0.f, 0.f, 0.f, 0.f};
; #pragma unroll
;         for (int n = 0; n < 4; ++n)
; #pragma unroll
;             for (int j = 0; j < 4; ++j) {
;                 const f32x4 a4 = mc[4 * j + n];
; #pragma unroll
;                 for (int np = 0; np < 4; ++np) na[np] = __builtin_amdgcn_mfma_f32_16x16x4f32(a4[np], acc[n][j], na[np], 0, 0, 0);
;             }
; #pragma unroll
;         for (int n = 0; n < 4; ++n) acc[n] = na[n];
; #pragma unroll
;         for (int i = 0; i < 16; ++i) mc[i] = mn[i];
;     }
; __device__ __forceinline__ void store_strip(const f32x4 (&acc)[4], float* dst) {
; #pragma unroll
;     for (int j = 0; j < 4; ++j) *(f32x4*)(dst + 4 * j) = (f32x4){acc[0][j], acc[1][j], acc[2][j], acc[3][j]};
; }
	v_mov_b32_e32 v128, v200
	v_mov_b32_e32 v129, v204
	v_mov_b32_e32 v130, v212
	v_mov_b32_e32 v131, v230
	v_mov_b32_e32 v132, v201
	v_mov_b32_e32 v133, v205
	v_mov_b32_e32 v134, v213
	v_mov_b32_e32 v135, v231
	v_mov_b32_e32 v136, v202
	v_mov_b32_e32 v137, v206
	v_mov_b32_e32 v138, v214
	v_mov_b32_e32 v139, v232
	v_mov_b32_e32 v140, v203
	v_mov_b32_e32 v141, v207
	v_mov_b32_e32 v142, v215
	v_mov_b32_e32 v143, v233
	v_mfma_f32_16x16x4_f32 v[128:131], v64, v168, v[128:131]
	v_mfma_f32_16x16x4_f32 v[132:135], v65, v168, v[132:135]
	v_mfma_f32_16x16x4_f32 v[136:139], v66, v168, v[136:139]
	v_mfma_f32_16x16x4_f32 v[140:143], v67, v168, v[140:143]
	v_mfma_f32_16x16x4_f32 v[128:131], v80, v169, v[128:131]
	v_mfma_f32_16x16x4_f32 v[132:135], v81, v169, v[132:135]
	v_mfma_f32_16x16x4_f32 v[136:139], v82, v169, v[136:139]
	v_mfma_f32_16x16x4_f32 v[140:143], v83, v169, v[140:143]
	v_mfma_f32_16x16x4_f32 v[128:131], v96, v170, v[128:131]
	v_mfma_f32_16x16x4_f32 v[132:135], v97, v170, v[132:135]
	v_mfma_f32_16x16x4_f32 v[136:139], v98, v170, v[136:139]
	v_mfma_f32_16x16x4_f32 v[140:143], v99, v170, v[140:143]
	v_mfma_f32_16x16x4_f32 v[128:131], v112, v171, v[128:131]
	v_mfma_f32_16x16x4_f32 v[132:135], v113, v171, v[132:135]
	v_mfma_f32_16x16x4_f32 v[136:139], v114, v171, v[136:139]
	v_mfma_f32_16x16x4_f32 v[140:143], v115, v171, v[140:143]
	v_mfma_f32_16x16x4_f32 v[128:131], v68, v172, v[128:131]
	v_mfma_f32_16x16x4_f32 v[132:135], v69, v172, v[132:135]
	v_mfma_f32_16x16x4_f32 v[136:139], v70, v172, v[136:139]
	v_mfma_f32_16x16x4_f32 v[140:143], v71, v172, v[140:143]
	v_mfma_f32_16x16x4_f32 v[128:131], v84, v173, v[128:131]
	v_mfma_f32_16x16x4_f32 v[132:135], v85, v173, v[132:135]
	v_mfma_f32_16x16x4_f32 v[136:139], v86, v173, v[136:139]
	v_mfma_f32_16x16x4_f32 v[140:143], v87, v173, v[140:143]
	v_mfma_f32_16x16x4_f32 v[128:131], v100, v174, v[128:131]
	v_mfma_f32_16x16x4_f32 v[132:135], v101, v174, v[132:135]
	v_mfma_f32_16x16x4_f32 v[136:139], v102, v174, v[136:139]
	v_mfma_f32_16x16x4_f32 v[140:143], v103, v174, v[140:143]
	v_mfma_f32_16x16x4_f32 v[128:131], v116, v175, v[128:131]
	v_mfma_f32_16x16x4_f32 v[132:135], v117, v175, v[132:135]
	v_mfma_f32_16x16x4_f32 v[136:139], v118, v175, v[136:139]
	v_mfma_f32_16x16x4_f32 v[140:143], v119, v175, v[140:143]
	v_mfma_f32_16x16x4_f32 v[128:131], v72, v176, v[128:131]
	v_mfma_f32_16x16x4_f32 v[132:135], v73, v176, v[132:135]
	v_mfma_f32_16x16x4_f32 v[136:139], v74, v176, v[136:139]
	v_mfma_f32_16x16x4_f32 v[140:143], v75, v176, v[140:143]
	v_mfma_f32_16x16x4_f32 v[128:131], v88, v177, v[128:131]
	v_mfma_f32_16x16x4_f32 v[132:135], v89, v177, v[132:135]
	v_mfma_f32_16x16x4_f32 v[136:139], v90, v177, v[136:139]
	v_mfma_f32_16x16x4_f32 v[140:143], v91, v177, v[140:143]
	v_mfma_f32_16x16x4_f32 v[128:131], v104, v178, v[128:131]
	v_mfma_f32_16x16x4_f32 v[132:135], v105, v178, v[132:135]
	v_mfma_f32_16x16x4_f32 v[136:139], v106, v178, v[136:139]
	v_mfma_f32_16x16x4_f32 v[140:143], v107, v178, v[140:143]
	v_mfma_f32_16x16x4_f32 v[128:131], v120, v179, v[128:131]
	v_mfma_f32_16x16x4_f32 v[132:135], v121, v179, v[132:135]
	v_mfma_f32_16x16x4_f32 v[136:139], v122, v179, v[136:139]
	v_mfma_f32_16x16x4_f32 v[140:143], v123, v179, v[140:143]
	v_mfma_f32_16x16x4_f32 v[128:131], v76, v180, v[128:131]
	v_mfma_f32_16x16x4_f32 v[132:135], v77, v180, v[132:135]
	v_mfma_f32_16x16x4_f32 v[136:139], v78, v180, v[136:139]
	v_mfma_f32_16x16x4_f32 v[140:143], v79, v180, v[140:143]
	v_mfma_f32_16x16x4_f32 v[128:131], v92, v181, v[128:131]
	v_mfma_f32_16x16x4_f32 v[132:135], v93, v181, v[132:135]
	v_mfma_f32_16x16x4_f32 v[136:139], v94, v181, v[136:139]
	v_mfma_f32_16x16x4_f32 v[140:143], v95, v181, v[140:143]
	v_mfma_f32_16x16x4_f32 v[128:131], v108, v182, v[128:131]
	v_mfma_f32_16x16x4_f32 v[132:135], v109, v182, v[132:135]
	v_mfma_f32_16x16x4_f32 v[136:139], v110, v182, v[136:139]
	v_mfma_f32_16x16x4_f32 v[140:143], v111, v182, v[140:143]
	v_mfma_f32_16x16x4_f32 v[128:131], v124, v183, v[128:131]
	v_mfma_f32_16x16x4_f32 v[132:135], v125, v183, v[132:135]
	v_mfma_f32_16x16x4_f32 v[136:139], v126, v183, v[136:139]
	v_mfma_f32_16x16x4_f32 v[140:143], v127, v183, v[140:143]
	s_mov_b64 s[0:1], s[4:5]
	s_mov_b64 s[2:3], s[6:7]
	s_add_i32 s9, s9, 1
	s_cmp_eq_u32 s9, 8
	s_cbranch_scc0 .Lp2_l0c_loop
	s_nop 7
	s_nop 3
	s_add_u32 s0, s72, 0x14a84000
	s_addc_u32 s1, s73, 0
.Lp2l0_st:
	s_add_u32 s0, s0, s18
	s_addc_u32 s1, s1, 0
	v_mov_b32_e32 v234, v128
	v_mov_b32_e32 v235, v132
	v_mov_b32_e32 v236, v136
	v_mov_b32_e32 v237, v140
	global_store_dwordx4 v145, v[234:237], s[0:1]
	v_mov_b32_e32 v238, v129
	v_mov_b32_e32 v239, v133
	v_mov_b32_e32 v240, v137
	v_mov_b32_e32 v241, v141
	global_store_dwordx4 v145, v[238:241], s[0:1] offset:16
	v_mov_b32_e32 v234, v130
	v_mov_b32_e32 v235, v134
	v_mov_b32_e32 v236, v138
	v_mov_b32_e32 v237, v142
	global_store_dwordx4 v145, v[234:237], s[0:1] offset:32
	v_mov_b32_e32 v238, v131
	v_mov_b32_e32 v239, v135
	v_mov_b32_e32 v240, v139
	v_mov_b32_e32 v241, v143
	global_store_dwordx4 v145, v[238:241], s[0:1] offset:48
	s_add_i32 s8, s8, s16
	s_cmpk_gt_i32 s8, 0x3ff
	s_cbranch_scc0 .Lp2l0_item
